# K-loops: s_setprio 1 moved before the pre-MFMA barrier, redundant post-barrier lgkmcnt(0) dropped; mixout epilogue second-half residual loads issued up front
# speedup vs baseline: 1.0042x; 1.0027x over previous
; #define PG8_STAGE(bufoff, gbase, voff) do { _Pragma("unroll") for (int _i = 0; _i < 2; ++_i) \
;         __builtin_amdgcn_global_load_lds((const unsigned*)((const char*)(gbase) + (voff)[_i]), (PG8_LAS unsigned*)(lds + (bufoff) + ldsw + _i * 8192), 16, 0, 0); } while (0)
; #define PG8_LDA(dst, b, h) do { _Pragma("unroll") for (int m = 0; m < 4; ++m) _Pragma("unroll") for (int k = 0; k < 2; ++k) dst[m][k] = *(const PG8_LAS bf16x8*)(lds + PG8_SA(b, h) + aoff + m * 2048 + k * 1024); } while (0)
; #define PG8_LDB(dst, b, h) do { _Pragma("unroll") for (int n = 0; n < 2; ++n) _Pragma("unroll") for (int k = 0; k < 2; ++k) dst[n][k] = *(const PG8_LAS bf16x8*)(lds + PG8_SB(b, h) + boff + n * 2048 + k * 1024); } while (0)
; #define PG8_MMA(ai, bj, At, Bt) do { __builtin_amdgcn_s_setprio(1); _Pragma("unroll") for (int m = 0; m < 4; ++m) _Pragma("unroll") for (int n = 0; n < 2; ++n) _Pragma("unroll") for (int k = 0; k < 2; ++k) \
;         acc[ai][bj][m][n] = __builtin_amdgcn_mfma_f32_16x16x32_bf16(Bt[n][k], At[m][k], acc[ai][bj][m][n], 0, 0, 0); __builtin_amdgcn_s_setprio(0); } while (0)
; #define PG8_WAIT_V(n) asm volatile("s_waitcnt vmcnt(" #n ")" ::: "memory")
; #define PG8_WAIT_L(n) asm volatile("s_waitcnt lgkmcnt(" #n ")" ::: "memory")
; template <class Epi, class Sched, bool ALIGN_EPI = false, bool SP2 = true>
; __device__ __forceinline__ void gemm_phase(PG8_LAS unsigned char* lds, const Gemm g, const Sched& S, const Epi& E) {
;     ...
;             const bool last = (t == nt - 2);
;             const char* a1 = cA + (size_t)(t + 1) * kstepA;
;             const char* a2 = last ? nA : cA + (size_t)(t + 2) * kstepA; const char* b2 = last ? nB : cB + (size_t)(t + 2) * kstep;
;             const char* a3 = a2 + kstepA; const char* b3 = b2 + kstep;
;             if (last && has_next) S.a_ready(nxt);
;             if constexpr (SP2) {
;             PG8_LDB(B0, 0, 0); PG8_LDB(B1, 0, 1); PG8_SCHED; PG8_LDA(At, 0, 0); PG8_STAGE(PG8_SA(1, 1), a1 + hstepA, voffA);
;             PG8_WAIT_V(8); PG8_WAIT_L(0); PG8_BAR; PG8_MMA(0, 0, At, B0); PG8_MMA(0, 1, At, B1); PG8_BAR; PG8_SCHED;
;             PG8_LDA(At, 0, 1); PG8_STAGE(PG8_SB(0, 0), b2, voffB); PG8_STAGE(PG8_SB(0, 1), b2 + hstep, voffB); PG8_STAGE(PG8_SA(0, 0), a2, voffA);
;             PG8_WAIT_V(8); PG8_WAIT_L(0); PG8_BAR; PG8_MMA(1, 0, At, B0); PG8_MMA(1, 1, At, B1); PG8_BAR; PG8_SCHED;
.LBB0_128:
	s_add_u32 s14, s46, 0xfffc0080
	s_addc_u32 s15, s47, -1
	s_add_i32 s70, 0, 0x10000
	s_cmp_eq_u32 s60, 12
	s_cselect_b32 s51, s17, s15
	s_cselect_b32 s50, s39, s14
	v_add_u32_e32 v141, s70, v147
	s_cselect_b32 s49, s25, s7
	s_cselect_b32 s48, s59, s6
	s_add_i32 s71, 0, 0x14000
	ds_read_b128 v[152:155], v141
	ds_read_b128 v[156:159], v141 offset:1024
	ds_read_b128 v[160:163], v141 offset:2048
	ds_read_b128 v[164:167], v141 offset:3072
	v_add_u32_e32 v141, s71, v147
	ds_read_b128 v[168:171], v141
	ds_read_b128 v[172:175], v141 offset:1024
	ds_read_b128 v[176:179], v141 offset:2048
	ds_read_b128 v[180:183], v141 offset:3072
	s_add_u32 s14, s6, 0x3ff80
	s_addc_u32 s15, s7, 0
	v_lshl_add_u64 v[148:149], s[14:15], 0, v[132:133]
	s_add_i32 m0, s28, 0x1c000
	ds_read_b128 v[184:187], v150
	ds_read_b128 v[188:191], v150 offset:1024
	ds_read_b128 v[200:203], v150 offset:2048
	ds_read_b128 v[204:207], v150 offset:3072
	ds_read_b128 v[208:211], v150 offset:4096
	ds_read_b128 v[212:215], v150 offset:5120
	ds_read_b128 v[216:219], v150 offset:6144
	ds_read_b128 v[220:223], v150 offset:7168
	global_load_lds_dwordx4 v[148:149], off
	v_lshl_add_u64 v[148:149], s[14:15], 0, v[128:129]
	s_add_i32 m0, s28, 0x1e000
	s_nop 0
	global_load_lds_dwordx4 v[148:149], off
	v_lshl_add_u64 v[148:149], s[46:47], 0, v[136:137]
	s_add_i32 m0, s29, 0xc000
	s_nop 0
	global_load_lds_dwordx4 v[148:149], off
	v_lshl_add_u64 v[148:149], s[46:47], 0, v[138:139]
	s_add_i32 m0, s29, 0xe000
	s_nop 0
	global_load_lds_dwordx4 v[148:149], off
	s_waitcnt vmcnt(8)
	s_waitcnt lgkmcnt(0)
	s_setprio 1
	s_barrier
	v_mfma_f32_16x16x32_bf16 v[120:123], v[152:155], v[184:187], v[120:123]
	v_mfma_f32_16x16x32_bf16 v[112:115], v[160:163], v[184:187], v[112:115]
	v_mfma_f32_16x16x32_bf16 v[108:111], v[152:155], v[200:203], v[108:111]
	v_mfma_f32_16x16x32_bf16 v[96:99], v[160:163], v[200:203], v[96:99]
	v_mfma_f32_16x16x32_bf16 v[92:95], v[152:155], v[208:211], v[92:95]
	v_mfma_f32_16x16x32_bf16 v[80:83], v[160:163], v[208:211], v[80:83]
	v_mfma_f32_16x16x32_bf16 v[76:79], v[152:155], v[216:219], v[76:79]
	v_mfma_f32_16x16x32_bf16 v[64:67], v[160:163], v[216:219], v[64:67]
	v_mfma_f32_16x16x32_bf16 v[120:123], v[156:159], v[188:191], v[120:123]
	v_mfma_f32_16x16x32_bf16 v[112:115], v[164:167], v[188:191], v[112:115]
	v_mfma_f32_16x16x32_bf16 v[108:111], v[156:159], v[204:207], v[108:111]
	v_mfma_f32_16x16x32_bf16 v[96:99], v[164:167], v[204:207], v[96:99]
	v_mfma_f32_16x16x32_bf16 v[92:95], v[156:159], v[212:215], v[92:95]
	v_mfma_f32_16x16x32_bf16 v[80:83], v[164:167], v[212:215], v[80:83]
	v_mfma_f32_16x16x32_bf16 v[76:79], v[156:159], v[220:223], v[76:79]
	v_mfma_f32_16x16x32_bf16 v[64:67], v[164:167], v[220:223], v[64:67]
	v_mfma_f32_16x16x32_bf16 v[124:127], v[168:171], v[184:187], v[124:127]
	v_mfma_f32_16x16x32_bf16 v[116:119], v[176:179], v[184:187], v[116:119]
	v_mfma_f32_16x16x32_bf16 v[104:107], v[168:171], v[200:203], v[104:107]
	v_mfma_f32_16x16x32_bf16 v[100:103], v[176:179], v[200:203], v[100:103]
	v_mfma_f32_16x16x32_bf16 v[88:91], v[168:171], v[208:211], v[88:91]
	v_mfma_f32_16x16x32_bf16 v[84:87], v[176:179], v[208:211], v[84:87]
	v_mfma_f32_16x16x32_bf16 v[72:75], v[168:171], v[216:219], v[72:75]
	v_mfma_f32_16x16x32_bf16 v[68:71], v[176:179], v[216:219], v[68:71]
	v_mfma_f32_16x16x32_bf16 v[124:127], v[172:175], v[188:191], v[124:127]
	v_mfma_f32_16x16x32_bf16 v[116:119], v[180:183], v[188:191], v[116:119]
	v_mfma_f32_16x16x32_bf16 v[104:107], v[172:175], v[204:207], v[104:107]
	v_mfma_f32_16x16x32_bf16 v[100:103], v[180:183], v[204:207], v[100:103]
	v_mfma_f32_16x16x32_bf16 v[88:91], v[172:175], v[212:215], v[88:91]
	v_mfma_f32_16x16x32_bf16 v[84:87], v[180:183], v[212:215], v[84:87]
	v_mfma_f32_16x16x32_bf16 v[72:75], v[172:175], v[220:223], v[72:75]
	v_mfma_f32_16x16x32_bf16 v[68:71], v[180:183], v[220:223], v[68:71]
	s_setprio 0
	s_barrier
	s_add_i32 s14, s70, s28
	v_lshl_add_u64 v[148:149], s[48:49], 0, v[132:133]
	s_mov_b32 m0, s14
	ds_read_b128 v[184:187], v150 offset:16384
	ds_read_b128 v[188:191], v150 offset:17408
	ds_read_b128 v[200:203], v150 offset:18432
	ds_read_b128 v[204:207], v150 offset:19456
	ds_read_b128 v[208:211], v150 offset:20480
	ds_read_b128 v[212:215], v150 offset:21504
	ds_read_b128 v[216:219], v150 offset:22528
	ds_read_b128 v[220:223], v150 offset:23552
	global_load_lds_dwordx4 v[148:149], off
	s_add_i32 m0, s14, 0x2000
	v_lshl_add_u64 v[224:225], s[48:49], 0, v[128:129]
	global_load_lds_dwordx4 v[224:225], off
	v_lshl_add_u64 v[234:235], s[50:51], 0, v[130:131]
	v_lshl_add_u64 v[226:227], s[50:51], 0, v[134:135]
	s_mov_b32 m0, s29
	s_nop 0
	global_load_lds_dwordx4 v[226:227], off
	s_mov_b32 m0, s30
	s_nop 0
	global_load_lds_dwordx4 v[234:235], off
	s_waitcnt vmcnt(6)
	s_waitcnt lgkmcnt(0)
	s_setprio 1
	s_barrier
; #define PG8_STAGE(bufoff, gbase, voff) do { _Pragma("unroll") for (int _i = 0; _i < 2; ++_i) \
;         __builtin_amdgcn_global_load_lds((const unsigned*)((const char*)(gbase) + (voff)[_i]), (PG8_LAS unsigned*)(lds + (bufoff) + ldsw + _i * 8192), 16, 0, 0); } while (0)
; #define PG8_LDA(dst, b, h) do { _Pragma("unroll") for (int m = 0; m < 4; ++m) _Pragma("unroll") for (int k = 0; k < 2; ++k) dst[m][k] = *(const PG8_LAS bf16x8*)(lds + PG8_SA(b, h) + aoff + m * 2048 + k * 1024); } while (0)
; #define PG8_LDB(dst, b, h) do { _Pragma("unroll") for (int n = 0; n < 2; ++n) _Pragma("unroll") for (int k = 0; k < 2; ++k) dst[n][k] = *(const PG8_LAS bf16x8*)(lds + PG8_SB(b, h) + boff + n * 2048 + k * 1024); } while (0)
; #define PG8_MMA(ai, bj, At, Bt) do { __builtin_amdgcn_s_setprio(1); _Pragma("unroll") for (int m = 0; m < 4; ++m) _Pragma("unroll") for (int n = 0; n < 2; ++n) _Pragma("unroll") for (int k = 0; k < 2; ++k) \
;         acc[ai][bj][m][n] = __builtin_amdgcn_mfma_f32_16x16x32_bf16(Bt[n][k], At[m][k], acc[ai][bj][m][n], 0, 0, 0); __builtin_amdgcn_s_setprio(0); } while (0)
; #define PG8_WAIT_V(n) asm volatile("s_waitcnt vmcnt(" #n ")" ::: "memory")
; #define PG8_WAIT_L(n) asm volatile("s_waitcnt lgkmcnt(" #n ")" ::: "memory")
; #define PG8_BAR __builtin_amdgcn_s_barrier()
; #define PG8_SCHED __builtin_amdgcn_sched_barrier(0)
; template <class Epi, class Sched, bool ALIGN_EPI = false, bool SP2 = true>
; __device__ __forceinline__ void gemm_phase(PG8_LAS unsigned char* lds, const Gemm g, const Sched& S, const Epi& E) {
;     ...
;             PG8_WAIT_V(8); PG8_WAIT_L(0); PG8_BAR; PG8_MMA(1, 0, At, B0); PG8_MMA(1, 1, At, B1); PG8_BAR; PG8_SCHED;
;             PG8_LDB(B0, 1, 0); PG8_LDB(B1, 1, 1); PG8_SCHED; PG8_LDA(At, 1, 0); PG8_STAGE(PG8_SA(0, 1), a2 + hstepA, voffA);
;             PG8_WAIT_V(8); PG8_WAIT_L(0); PG8_BAR; PG8_MMA(0, 0, At, B0); PG8_MMA(0, 1, At, B1); PG8_BAR; PG8_SCHED;
	v_mfma_f32_16x16x32_bf16 v[60:63], v[152:155], v[184:187], v[60:63]
	v_mfma_f32_16x16x32_bf16 v[48:51], v[160:163], v[184:187], v[48:51]
	v_mfma_f32_16x16x32_bf16 v[44:47], v[152:155], v[200:203], v[44:47]
	v_mfma_f32_16x16x32_bf16 v[32:35], v[160:163], v[200:203], v[32:35]
	v_mfma_f32_16x16x32_bf16 v[28:31], v[152:155], v[208:211], v[28:31]
	v_mfma_f32_16x16x32_bf16 v[16:19], v[160:163], v[208:211], v[16:19]
	v_mfma_f32_16x16x32_bf16 v[12:15], v[152:155], v[216:219], v[12:15]
	v_mfma_f32_16x16x32_bf16 v[4:7], v[160:163], v[216:219], v[4:7]
	v_mfma_f32_16x16x32_bf16 v[60:63], v[156:159], v[188:191], v[60:63]
	v_mfma_f32_16x16x32_bf16 v[48:51], v[164:167], v[188:191], v[48:51]
	v_mfma_f32_16x16x32_bf16 v[44:47], v[156:159], v[204:207], v[44:47]
	v_mfma_f32_16x16x32_bf16 v[32:35], v[164:167], v[204:207], v[32:35]
	v_mfma_f32_16x16x32_bf16 v[28:31], v[156:159], v[212:215], v[28:31]
	v_mfma_f32_16x16x32_bf16 v[16:19], v[164:167], v[212:215], v[16:19]
	v_mfma_f32_16x16x32_bf16 v[12:15], v[156:159], v[220:223], v[12:15]
	v_mfma_f32_16x16x32_bf16 v[4:7], v[164:167], v[220:223], v[4:7]
	v_mfma_f32_16x16x32_bf16 v[56:59], v[168:171], v[184:187], v[56:59]
	v_mfma_f32_16x16x32_bf16 v[52:55], v[176:179], v[184:187], v[52:55]
	v_mfma_f32_16x16x32_bf16 v[40:43], v[168:171], v[200:203], v[40:43]
	v_mfma_f32_16x16x32_bf16 v[36:39], v[176:179], v[200:203], v[36:39]
	v_mfma_f32_16x16x32_bf16 v[24:27], v[168:171], v[208:211], v[24:27]
	v_mfma_f32_16x16x32_bf16 v[20:23], v[176:179], v[208:211], v[20:23]
	v_mfma_f32_16x16x32_bf16 v[8:11], v[168:171], v[216:219], v[8:11]
	v_mfma_f32_16x16x32_bf16 v[0:3], v[176:179], v[216:219], v[0:3]
	v_mfma_f32_16x16x32_bf16 v[56:59], v[172:175], v[188:191], v[56:59]
	v_mfma_f32_16x16x32_bf16 v[52:55], v[180:183], v[188:191], v[52:55]
	v_mfma_f32_16x16x32_bf16 v[40:43], v[172:175], v[204:207], v[40:43]
	v_mfma_f32_16x16x32_bf16 v[36:39], v[180:183], v[204:207], v[36:39]
	v_mfma_f32_16x16x32_bf16 v[24:27], v[172:175], v[212:215], v[24:27]
	v_mfma_f32_16x16x32_bf16 v[20:23], v[180:183], v[212:215], v[20:23]
	v_mfma_f32_16x16x32_bf16 v[8:11], v[172:175], v[220:223], v[8:11]
	v_mfma_f32_16x16x32_bf16 v[0:3], v[180:183], v[220:223], v[0:3]
	s_setprio 0
	s_barrier
	s_add_i32 s70, 0, 0x18000
	v_add_u32_e32 v141, s70, v147
	s_add_i32 s71, 0, 0x1c000
	ds_read_b128 v[152:155], v141
	ds_read_b128 v[156:159], v141 offset:1024
	ds_read_b128 v[160:163], v141 offset:2048
	ds_read_b128 v[164:167], v141 offset:3072
	v_add_u32_e32 v141, s71, v147
	ds_read_b128 v[168:171], v141
	ds_read_b128 v[172:175], v141 offset:1024
	ds_read_b128 v[176:179], v141 offset:2048
	ds_read_b128 v[180:183], v141 offset:3072
	s_add_u32 s14, s48, 0x40000
	s_addc_u32 s15, s49, 0
	s_add_i32 m0, s28, 0x14000
	v_lshl_add_u64 v[236:237], s[14:15], 0, v[132:133]
	ds_read_b128 v[184:187], v150 offset:32768
	ds_read_b128 v[188:191], v150 offset:33792
	ds_read_b128 v[200:203], v150 offset:34816
	ds_read_b128 v[204:207], v150 offset:35840
	ds_read_b128 v[208:211], v150 offset:36864
	ds_read_b128 v[212:215], v150 offset:37888
	ds_read_b128 v[216:219], v150 offset:38912
	ds_read_b128 v[220:223], v150 offset:39936
	global_load_lds_dwordx4 v[236:237], off
	v_lshl_add_u64 v[236:237], s[14:15], 0, v[128:129]
	s_add_i32 m0, s28, 0x16000
	s_add_u32 s14, s50, 0x40000
	s_addc_u32 s15, s51, 0
	global_load_lds_dwordx4 v[236:237], off
	v_lshl_add_u64 v[236:237], s[14:15], 0, v[134:135]
	s_mov_b32 m0, s31
	s_nop 0
	global_load_lds_dwordx4 v[236:237], off
	v_lshl_add_u64 v[236:237], s[14:15], 0, v[130:131]
	s_mov_b32 m0, s34
	s_nop 0
	global_load_lds_dwordx4 v[236:237], off
	s_waitcnt vmcnt(8)
	s_waitcnt lgkmcnt(0)
	s_setprio 1
	s_barrier
; #define PG8_STAGE(bufoff, gbase, voff) do { _Pragma("unroll") for (int _i = 0; _i < 2; ++_i) \
;         __builtin_amdgcn_global_load_lds((const unsigned*)((const char*)(gbase) + (voff)[_i]), (PG8_LAS unsigned*)(lds + (bufoff) + ldsw + _i * 8192), 16, 0, 0); } while (0)
; #define PG8_LDA(dst, b, h) do { _Pragma("unroll") for (int m = 0; m < 4; ++m) _Pragma("unroll") for (int k = 0; k < 2; ++k) dst[m][k] = *(const PG8_LAS bf16x8*)(lds + PG8_SA(b, h) + aoff + m * 2048 + k * 1024); } while (0)
; #define PG8_MMA(ai, bj, At, Bt) do { __builtin_amdgcn_s_setprio(1); _Pragma("unroll") for (int m = 0; m < 4; ++m) _Pragma("unroll") for (int n = 0; n < 2; ++n) _Pragma("unroll") for (int k = 0; k < 2; ++k) \
;         acc[ai][bj][m][n] = __builtin_amdgcn_mfma_f32_16x16x32_bf16(Bt[n][k], At[m][k], acc[ai][bj][m][n], 0, 0, 0); __builtin_amdgcn_s_setprio(0); } while (0)
; #define PG8_WAIT_V(n) asm volatile("s_waitcnt vmcnt(" #n ")" ::: "memory")
; #define PG8_WAIT_L(n) asm volatile("s_waitcnt lgkmcnt(" #n ")" ::: "memory")
; #define PG8_BAR __builtin_amdgcn_s_barrier()
; #define PG8_SCHED __builtin_amdgcn_sched_barrier(0)
; template <class Epi, class Sched, bool ALIGN_EPI = false, bool SP2 = true>
; __device__ __forceinline__ void gemm_phase(PG8_LAS unsigned char* lds, const Gemm g, const Sched& S, const Epi& E) {
;     ...
;         for (int t = 0; t < nt; t += 2) {
;     ...
;             PG8_WAIT_V(8); PG8_WAIT_L(0); PG8_BAR; PG8_MMA(0, 0, At, B0); PG8_MMA(0, 1, At, B1); PG8_BAR; PG8_SCHED;
;             PG8_LDA(At, 1, 1); PG8_STAGE(PG8_SB(1, 0), b3, voffB); PG8_STAGE(PG8_SB(1, 1), b3 + hstep, voffB); PG8_STAGE(PG8_SA(1, 0), a3, voffA);
;             PG8_WAIT_V(8); PG8_WAIT_L(0); PG8_BAR; PG8_MMA(1, 0, At, B0); PG8_MMA(1, 1, At, B1); PG8_BAR; PG8_SCHED;
	v_mfma_f32_16x16x32_bf16 v[120:123], v[152:155], v[184:187], v[120:123]
	v_mfma_f32_16x16x32_bf16 v[112:115], v[160:163], v[184:187], v[112:115]
	v_mfma_f32_16x16x32_bf16 v[108:111], v[152:155], v[200:203], v[108:111]
	v_mfma_f32_16x16x32_bf16 v[96:99], v[160:163], v[200:203], v[96:99]
	v_mfma_f32_16x16x32_bf16 v[92:95], v[152:155], v[208:211], v[92:95]
	v_mfma_f32_16x16x32_bf16 v[80:83], v[160:163], v[208:211], v[80:83]
	v_mfma_f32_16x16x32_bf16 v[76:79], v[152:155], v[216:219], v[76:79]
	v_mfma_f32_16x16x32_bf16 v[64:67], v[160:163], v[216:219], v[64:67]
	v_mfma_f32_16x16x32_bf16 v[120:123], v[156:159], v[188:191], v[120:123]
	v_mfma_f32_16x16x32_bf16 v[112:115], v[164:167], v[188:191], v[112:115]
	v_mfma_f32_16x16x32_bf16 v[108:111], v[156:159], v[204:207], v[108:111]
	v_mfma_f32_16x16x32_bf16 v[96:99], v[164:167], v[204:207], v[96:99]
	v_mfma_f32_16x16x32_bf16 v[92:95], v[156:159], v[212:215], v[92:95]
	v_mfma_f32_16x16x32_bf16 v[80:83], v[164:167], v[212:215], v[80:83]
	v_mfma_f32_16x16x32_bf16 v[76:79], v[156:159], v[220:223], v[76:79]
	v_mfma_f32_16x16x32_bf16 v[64:67], v[164:167], v[220:223], v[64:67]
	v_mfma_f32_16x16x32_bf16 v[124:127], v[168:171], v[184:187], v[124:127]
	v_mfma_f32_16x16x32_bf16 v[116:119], v[176:179], v[184:187], v[116:119]
	v_mfma_f32_16x16x32_bf16 v[104:107], v[168:171], v[200:203], v[104:107]
	v_mfma_f32_16x16x32_bf16 v[100:103], v[176:179], v[200:203], v[100:103]
	v_mfma_f32_16x16x32_bf16 v[88:91], v[168:171], v[208:211], v[88:91]
	v_mfma_f32_16x16x32_bf16 v[84:87], v[176:179], v[208:211], v[84:87]
	v_mfma_f32_16x16x32_bf16 v[72:75], v[168:171], v[216:219], v[72:75]
	v_mfma_f32_16x16x32_bf16 v[68:71], v[176:179], v[216:219], v[68:71]
	v_mfma_f32_16x16x32_bf16 v[124:127], v[172:175], v[188:191], v[124:127]
	v_mfma_f32_16x16x32_bf16 v[116:119], v[180:183], v[188:191], v[116:119]
	v_mfma_f32_16x16x32_bf16 v[104:107], v[172:175], v[204:207], v[104:107]
	v_mfma_f32_16x16x32_bf16 v[100:103], v[180:183], v[204:207], v[100:103]
	v_mfma_f32_16x16x32_bf16 v[88:91], v[172:175], v[212:215], v[88:91]
	v_mfma_f32_16x16x32_bf16 v[84:87], v[180:183], v[212:215], v[84:87]
	v_mfma_f32_16x16x32_bf16 v[72:75], v[172:175], v[220:223], v[72:75]
	v_mfma_f32_16x16x32_bf16 v[68:71], v[180:183], v[220:223], v[68:71]
	s_setprio 0
	s_barrier
	s_add_i32 s14, s70, s28
	v_lshl_add_u64 v[148:149], v[148:149], 0, s[18:19]
	s_mov_b32 m0, s14
	ds_read_b128 v[184:187], v150 offset:49152
	ds_read_b128 v[188:191], v150 offset:50176
	ds_read_b128 v[200:203], v150 offset:51200
	ds_read_b128 v[204:207], v150 offset:52224
	ds_read_b128 v[208:211], v150 offset:53248
	ds_read_b128 v[212:215], v150 offset:54272
	ds_read_b128 v[216:219], v150 offset:55296
	ds_read_b128 v[220:223], v150 offset:56320
	global_load_lds_dwordx4 v[148:149], off
	s_add_i32 m0, s14, 0x2000
	v_lshl_add_u64 v[148:149], v[224:225], 0, s[18:19]
	global_load_lds_dwordx4 v[148:149], off
	v_lshl_add_u64 v[148:149], v[226:227], 0, s[18:19]
	s_mov_b32 m0, s52
	s_nop 0
	global_load_lds_dwordx4 v[148:149], off
	v_lshl_add_u64 v[148:149], v[234:235], 0, s[18:19]
	s_mov_b32 m0, s53
	s_nop 0
	global_load_lds_dwordx4 v[148:149], off
	s_waitcnt vmcnt(6)
	s_waitcnt lgkmcnt(0)
	s_setprio 1
	s_barrier
	v_mfma_f32_16x16x32_bf16 v[60:63], v[152:155], v[184:187], v[60:63]
	v_mfma_f32_16x16x32_bf16 v[48:51], v[160:163], v[184:187], v[48:51]
	v_mfma_f32_16x16x32_bf16 v[44:47], v[152:155], v[200:203], v[44:47]
	v_mfma_f32_16x16x32_bf16 v[32:35], v[160:163], v[200:203], v[32:35]
	v_mfma_f32_16x16x32_bf16 v[28:31], v[152:155], v[208:211], v[28:31]
	v_mfma_f32_16x16x32_bf16 v[16:19], v[160:163], v[208:211], v[16:19]
	v_mfma_f32_16x16x32_bf16 v[12:15], v[152:155], v[216:219], v[12:15]
	v_mfma_f32_16x16x32_bf16 v[4:7], v[160:163], v[216:219], v[4:7]
	v_mfma_f32_16x16x32_bf16 v[60:63], v[156:159], v[188:191], v[60:63]
	v_mfma_f32_16x16x32_bf16 v[48:51], v[164:167], v[188:191], v[48:51]
	v_mfma_f32_16x16x32_bf16 v[44:47], v[156:159], v[204:207], v[44:47]
	v_mfma_f32_16x16x32_bf16 v[32:35], v[164:167], v[204:207], v[32:35]
	v_mfma_f32_16x16x32_bf16 v[28:31], v[156:159], v[212:215], v[28:31]
	v_mfma_f32_16x16x32_bf16 v[16:19], v[164:167], v[212:215], v[16:19]
	v_mfma_f32_16x16x32_bf16 v[12:15], v[156:159], v[220:223], v[12:15]
	v_mfma_f32_16x16x32_bf16 v[4:7], v[164:167], v[220:223], v[4:7]
	v_mfma_f32_16x16x32_bf16 v[56:59], v[168:171], v[184:187], v[56:59]
	v_mfma_f32_16x16x32_bf16 v[52:55], v[176:179], v[184:187], v[52:55]
	v_mfma_f32_16x16x32_bf16 v[40:43], v[168:171], v[200:203], v[40:43]
	v_mfma_f32_16x16x32_bf16 v[36:39], v[176:179], v[200:203], v[36:39]
	v_mfma_f32_16x16x32_bf16 v[24:27], v[168:171], v[208:211], v[24:27]
	v_mfma_f32_16x16x32_bf16 v[20:23], v[176:179], v[208:211], v[20:23]
	v_mfma_f32_16x16x32_bf16 v[8:11], v[168:171], v[216:219], v[8:11]
	v_mfma_f32_16x16x32_bf16 v[0:3], v[176:179], v[216:219], v[0:3]
	v_mfma_f32_16x16x32_bf16 v[56:59], v[172:175], v[188:191], v[56:59]
	v_mfma_f32_16x16x32_bf16 v[52:55], v[180:183], v[188:191], v[52:55]
	v_mfma_f32_16x16x32_bf16 v[40:43], v[172:175], v[204:207], v[40:43]
	v_mfma_f32_16x16x32_bf16 v[36:39], v[180:183], v[204:207], v[36:39]
	v_mfma_f32_16x16x32_bf16 v[24:27], v[172:175], v[212:215], v[24:27]
	v_mfma_f32_16x16x32_bf16 v[20:23], v[180:183], v[212:215], v[20:23]
	v_mfma_f32_16x16x32_bf16 v[8:11], v[172:175], v[220:223], v[8:11]
	v_mfma_f32_16x16x32_bf16 v[0:3], v[180:183], v[220:223], v[0:3]
	s_setprio 0
	s_barrier
	s_add_i32 s60, s60, 2
	s_add_u32 s46, s46, 0x100
	s_addc_u32 s47, s47, 0
	s_add_u32 s6, s6, 0x100
	s_addc_u32 s7, s7, 0
	s_cmp_gt_u32 s60, 13
	s_cbranch_scc0 .LBB0_128
	s_and_b64 vcc, exec, s[20:21]
	s_cbranch_vccz .LBB0_131
	s_barrier

; #define PG8_STAGE(bufoff, gbase, voff) do { _Pragma("unroll") for (int _i = 0; _i < 2; ++_i) \
;         __builtin_amdgcn_global_load_lds((const unsigned*)((const char*)(gbase) + (voff)[_i]), (PG8_LAS unsigned*)(lds + (bufoff) + ldsw + _i * 8192), 16, 0, 0); } while (0)
; #define PG8_LDA(dst, b, h) do { _Pragma("unroll") for (int m = 0; m < 4; ++m) _Pragma("unroll") for (int k = 0; k < 2; ++k) dst[m][k] = *(const PG8_LAS bf16x8*)(lds + PG8_SA(b, h) + aoff + m * 2048 + k * 1024); } while (0)
; #define PG8_LDB(dst, b, h) do { _Pragma("unroll") for (int n = 0; n < 2; ++n) _Pragma("unroll") for (int k = 0; k < 2; ++k) dst[n][k] = *(const PG8_LAS bf16x8*)(lds + PG8_SB(b, h) + boff + n * 2048 + k * 1024); } while (0)
; #define PG8_MMA(ai, bj, At, Bt) do { __builtin_amdgcn_s_setprio(1); _Pragma("unroll") for (int m = 0; m < 4; ++m) _Pragma("unroll") for (int n = 0; n < 2; ++n) _Pragma("unroll") for (int k = 0; k < 2; ++k) \
;         acc[ai][bj][m][n] = __builtin_amdgcn_mfma_f32_16x16x32_bf16(Bt[n][k], At[m][k], acc[ai][bj][m][n], 0, 0, 0); __builtin_amdgcn_s_setprio(0); } while (0)
; #define PG8_WAIT_V(n) asm volatile("s_waitcnt vmcnt(" #n ")" ::: "memory")
; #define PG8_WAIT_L(n) asm volatile("s_waitcnt lgkmcnt(" #n ")" ::: "memory")
; template <class Epi, class Sched, bool ALIGN_EPI = false, bool SP2 = true>
; __device__ __forceinline__ void gemm_phase(PG8_LAS unsigned char* lds, const Gemm g, const Sched& S, const Epi& E) {
;     ...
;             const bool last = (t == nt - 2);
;             const char* a1 = cA + (size_t)(t + 1) * kstepA;
;             const char* a2 = last ? nA : cA + (size_t)(t + 2) * kstepA; const char* b2 = last ? nB : cB + (size_t)(t + 2) * kstep;
;             const char* a3 = a2 + kstepA; const char* b3 = b2 + kstep;
;             if (last && has_next) S.a_ready(nxt);
;             if constexpr (SP2) {
;             PG8_LDB(B0, 0, 0); PG8_LDB(B1, 0, 1); PG8_SCHED; PG8_LDA(At, 0, 0); PG8_STAGE(PG8_SA(1, 1), a1 + hstepA, voffA);
;             PG8_WAIT_V(8); PG8_WAIT_L(0); PG8_BAR; PG8_MMA(0, 0, At, B0); PG8_MMA(0, 1, At, B1); PG8_BAR; PG8_SCHED;
;             PG8_LDA(At, 0, 1); PG8_STAGE(PG8_SB(0, 0), b2, voffB); PG8_STAGE(PG8_SB(0, 1), b2 + hstep, voffB); PG8_STAGE(PG8_SA(0, 0), a2, voffA);
;             PG8_WAIT_V(8); PG8_WAIT_L(0); PG8_BAR; PG8_MMA(1, 0, At, B0); PG8_MMA(1, 1, At, B1); PG8_BAR; PG8_SCHED;
.LBB0_236:
	s_add_u32 s14, s42, 0x4000
	s_addc_u32 s15, s43, 0
	s_cmp_eq_u32 s7, 40
	s_cselect_b32 s84, s10, s14
	s_cselect_b32 s85, s11, s15
	s_cselect_b32 vcc_lo, s52, s17
	s_cselect_b32 vcc_hi, s53, s6
	s_add_u32 s46, s84, 0x8000
	s_addc_u32 s47, s85, 0
	s_add_i32 s14, 0, 0x10000
	s_add_i32 s4, 0, 0x14000
	v_add_u32_e32 v140, s14, v235
	v_add_u32_e32 v156, s4, v235
	ds_read_b128 v[128:131], v140
	ds_read_b128 v[132:135], v140 offset:1024
	ds_read_b128 v[136:139], v140 offset:2048
	ds_read_b128 v[140:143], v140 offset:3072
	ds_read_b128 v[144:147], v156
	ds_read_b128 v[148:151], v156 offset:1024
	ds_read_b128 v[152:155], v156 offset:2048
	ds_read_b128 v[156:159], v156 offset:3072
	v_lshl_add_u64 v[212:213], s[42:43], 0, v[208:209]
	s_add_i32 m0, s59, 0xc000
	ds_read_b128 v[160:163], v237
	ds_read_b128 v[164:167], v237 offset:1024
	ds_read_b128 v[168:171], v237 offset:2048
	ds_read_b128 v[172:175], v237 offset:3072
	ds_read_b128 v[176:179], v237 offset:4096
	ds_read_b128 v[180:183], v237 offset:5120
	ds_read_b128 v[184:187], v237 offset:6144
	ds_read_b128 v[188:191], v237 offset:7168
	global_load_lds_dwordx4 v[212:213], off
	v_lshl_add_u64 v[212:213], s[42:43], 0, v[210:211]
	s_add_i32 m0, s59, 0xe000
	s_nop 0
	global_load_lds_dwordx4 v[212:213], off
	s_waitcnt vmcnt(8)
	s_waitcnt lgkmcnt(0)
	s_setprio 1
	s_barrier
	v_mfma_f32_16x16x32_bf16 v[124:127], v[128:131], v[160:163], v[124:127]
	v_mfma_f32_16x16x32_bf16 v[120:123], v[136:139], v[160:163], v[120:123]
	v_mfma_f32_16x16x32_bf16 v[108:111], v[128:131], v[168:171], v[108:111]
	v_mfma_f32_16x16x32_bf16 v[104:107], v[136:139], v[168:171], v[104:107]
	v_mfma_f32_16x16x32_bf16 v[92:95], v[128:131], v[176:179], v[92:95]
	v_mfma_f32_16x16x32_bf16 v[88:91], v[136:139], v[176:179], v[88:91]
	v_mfma_f32_16x16x32_bf16 v[76:79], v[128:131], v[184:187], v[76:79]
	v_mfma_f32_16x16x32_bf16 v[72:75], v[136:139], v[184:187], v[72:75]
	v_mfma_f32_16x16x32_bf16 v[124:127], v[132:135], v[164:167], v[124:127]
	v_mfma_f32_16x16x32_bf16 v[120:123], v[140:143], v[164:167], v[120:123]
	v_mfma_f32_16x16x32_bf16 v[108:111], v[132:135], v[172:175], v[108:111]
	v_mfma_f32_16x16x32_bf16 v[104:107], v[140:143], v[172:175], v[104:107]
	v_mfma_f32_16x16x32_bf16 v[92:95], v[132:135], v[180:183], v[92:95]
	v_mfma_f32_16x16x32_bf16 v[88:91], v[140:143], v[180:183], v[88:91]
	v_mfma_f32_16x16x32_bf16 v[76:79], v[132:135], v[188:191], v[76:79]
	v_mfma_f32_16x16x32_bf16 v[72:75], v[140:143], v[188:191], v[72:75]
	s_setprio 0
	s_setprio 1
	v_mfma_f32_16x16x32_bf16 v[116:119], v[144:147], v[160:163], v[116:119]
	v_mfma_f32_16x16x32_bf16 v[112:115], v[152:155], v[160:163], v[112:115]
	v_mfma_f32_16x16x32_bf16 v[100:103], v[144:147], v[168:171], v[100:103]
	v_mfma_f32_16x16x32_bf16 v[96:99], v[152:155], v[168:171], v[96:99]
	v_mfma_f32_16x16x32_bf16 v[84:87], v[144:147], v[176:179], v[84:87]
	v_mfma_f32_16x16x32_bf16 v[80:83], v[152:155], v[176:179], v[80:83]
	v_mfma_f32_16x16x32_bf16 v[68:71], v[144:147], v[184:187], v[68:71]
	v_mfma_f32_16x16x32_bf16 v[64:67], v[152:155], v[184:187], v[64:67]
	v_mfma_f32_16x16x32_bf16 v[116:119], v[148:151], v[164:167], v[116:119]
	v_mfma_f32_16x16x32_bf16 v[112:115], v[156:159], v[164:167], v[112:115]
	v_mfma_f32_16x16x32_bf16 v[100:103], v[148:151], v[172:175], v[100:103]
	v_mfma_f32_16x16x32_bf16 v[96:99], v[156:159], v[172:175], v[96:99]
	v_mfma_f32_16x16x32_bf16 v[84:87], v[148:151], v[180:183], v[84:87]
	v_mfma_f32_16x16x32_bf16 v[80:83], v[156:159], v[180:183], v[80:83]
	v_mfma_f32_16x16x32_bf16 v[68:71], v[148:151], v[188:191], v[68:71]
	v_mfma_f32_16x16x32_bf16 v[64:67], v[156:159], v[188:191], v[64:67]
	s_setprio 0
	s_barrier
	s_add_i32 s5, s14, s57
	v_lshl_add_u64 v[212:213], vcc, 0, v[194:195]
	s_mov_b32 m0, s5
	ds_read_b128 v[160:163], v237 offset:16384
	ds_read_b128 v[164:167], v237 offset:17408
	ds_read_b128 v[168:171], v237 offset:18432
	ds_read_b128 v[172:175], v237 offset:19456
	ds_read_b128 v[176:179], v237 offset:20480
	ds_read_b128 v[180:183], v237 offset:21504
	ds_read_b128 v[184:187], v237 offset:22528
	ds_read_b128 v[188:191], v237 offset:23552
	global_load_lds_dwordx4 v[212:213], off
	s_add_i32 m0, s5, 0x2000
	s_add_u32 s14, vcc_lo, 0xb0000
	v_lshl_add_u64 v[214:215], vcc, 0, v[204:205]
	s_addc_u32 s15, vcc_hi, 0
	s_add_i32 s4, s4, s57
	global_load_lds_dwordx4 v[214:215], off
	v_lshl_add_u64 v[216:217], s[14:15], 0, v[194:195]
	s_mov_b32 m0, s4
	s_nop 0
	global_load_lds_dwordx4 v[216:217], off
	v_lshl_add_u64 v[216:217], s[14:15], 0, v[204:205]
	s_add_i32 m0, s4, 0x2000
	s_nop 0
	global_load_lds_dwordx4 v[216:217], off
	v_lshl_add_u64 v[216:217], s[84:85], 0, v[200:201]
	s_mov_b32 m0, s59
	s_nop 0
	global_load_lds_dwordx4 v[216:217], off
	v_lshl_add_u64 v[216:217], s[84:85], 0, v[202:203]
	s_mov_b32 m0, s60
	s_nop 0
	global_load_lds_dwordx4 v[216:217], off
	s_waitcnt vmcnt(8)
	s_waitcnt lgkmcnt(0)
	s_setprio 1
	s_barrier
; #define PG8_STAGE(bufoff, gbase, voff) do { _Pragma("unroll") for (int _i = 0; _i < 2; ++_i) \
;         __builtin_amdgcn_global_load_lds((const unsigned*)((const char*)(gbase) + (voff)[_i]), (PG8_LAS unsigned*)(lds + (bufoff) + ldsw + _i * 8192), 16, 0, 0); } while (0)
; #define PG8_LDA(dst, b, h) do { _Pragma("unroll") for (int m = 0; m < 4; ++m) _Pragma("unroll") for (int k = 0; k < 2; ++k) dst[m][k] = *(const PG8_LAS bf16x8*)(lds + PG8_SA(b, h) + aoff + m * 2048 + k * 1024); } while (0)
; #define PG8_LDB(dst, b, h) do { _Pragma("unroll") for (int n = 0; n < 2; ++n) _Pragma("unroll") for (int k = 0; k < 2; ++k) dst[n][k] = *(const PG8_LAS bf16x8*)(lds + PG8_SB(b, h) + boff + n * 2048 + k * 1024); } while (0)
; #define PG8_MMA(ai, bj, At, Bt) do { __builtin_amdgcn_s_setprio(1); _Pragma("unroll") for (int m = 0; m < 4; ++m) _Pragma("unroll") for (int n = 0; n < 2; ++n) _Pragma("unroll") for (int k = 0; k < 2; ++k) \
;         acc[ai][bj][m][n] = __builtin_amdgcn_mfma_f32_16x16x32_bf16(Bt[n][k], At[m][k], acc[ai][bj][m][n], 0, 0, 0); __builtin_amdgcn_s_setprio(0); } while (0)
; #define PG8_WAIT_V(n) asm volatile("s_waitcnt vmcnt(" #n ")" ::: "memory")
; #define PG8_WAIT_L(n) asm volatile("s_waitcnt lgkmcnt(" #n ")" ::: "memory")
; #define PG8_BAR __builtin_amdgcn_s_barrier()
; #define PG8_SCHED __builtin_amdgcn_sched_barrier(0)
; template <class Epi, class Sched, bool ALIGN_EPI = false, bool SP2 = true>
; __device__ __forceinline__ void gemm_phase(PG8_LAS unsigned char* lds, const Gemm g, const Sched& S, const Epi& E) {
;     ...
;             PG8_WAIT_V(8); PG8_WAIT_L(0); PG8_BAR; PG8_MMA(1, 0, At, B0); PG8_MMA(1, 1, At, B1); PG8_BAR; PG8_SCHED;
;             PG8_LDB(B0, 1, 0); PG8_LDB(B1, 1, 1); PG8_SCHED; PG8_LDA(At, 1, 0); PG8_STAGE(PG8_SA(0, 1), a2 + hstepA, voffA);
;             PG8_WAIT_V(8); PG8_WAIT_L(0); PG8_BAR; PG8_MMA(0, 0, At, B0); PG8_MMA(0, 1, At, B1); PG8_BAR; PG8_SCHED;
;             PG8_LDA(At, 1, 1); PG8_STAGE(PG8_SB(1, 0), b3, voffB); PG8_STAGE(PG8_SB(1, 1), b3 + hstep, voffB); PG8_STAGE(PG8_SA(1, 0), a3, voffA);
	v_mfma_f32_16x16x32_bf16 v[60:63], v[128:131], v[160:163], v[60:63]
	v_mfma_f32_16x16x32_bf16 v[56:59], v[136:139], v[160:163], v[56:59]
	v_mfma_f32_16x16x32_bf16 v[44:47], v[128:131], v[168:171], v[44:47]
	v_mfma_f32_16x16x32_bf16 v[40:43], v[136:139], v[168:171], v[40:43]
	v_mfma_f32_16x16x32_bf16 v[28:31], v[128:131], v[176:179], v[28:31]
	v_mfma_f32_16x16x32_bf16 v[24:27], v[136:139], v[176:179], v[24:27]
	v_mfma_f32_16x16x32_bf16 v[12:15], v[128:131], v[184:187], v[12:15]
	v_mfma_f32_16x16x32_bf16 v[8:11], v[136:139], v[184:187], v[8:11]
	v_mfma_f32_16x16x32_bf16 v[60:63], v[132:135], v[164:167], v[60:63]
	v_mfma_f32_16x16x32_bf16 v[56:59], v[140:143], v[164:167], v[56:59]
	v_mfma_f32_16x16x32_bf16 v[44:47], v[132:135], v[172:175], v[44:47]
	v_mfma_f32_16x16x32_bf16 v[40:43], v[140:143], v[172:175], v[40:43]
	v_mfma_f32_16x16x32_bf16 v[28:31], v[132:135], v[180:183], v[28:31]
	v_mfma_f32_16x16x32_bf16 v[24:27], v[140:143], v[180:183], v[24:27]
	v_mfma_f32_16x16x32_bf16 v[12:15], v[132:135], v[188:191], v[12:15]
	v_mfma_f32_16x16x32_bf16 v[8:11], v[140:143], v[188:191], v[8:11]
	s_setprio 0
	s_setprio 1
	v_mfma_f32_16x16x32_bf16 v[52:55], v[144:147], v[160:163], v[52:55]
	v_mfma_f32_16x16x32_bf16 v[48:51], v[152:155], v[160:163], v[48:51]
	v_mfma_f32_16x16x32_bf16 v[36:39], v[144:147], v[168:171], v[36:39]
	v_mfma_f32_16x16x32_bf16 v[32:35], v[152:155], v[168:171], v[32:35]
	v_mfma_f32_16x16x32_bf16 v[20:23], v[144:147], v[176:179], v[20:23]
	v_mfma_f32_16x16x32_bf16 v[16:19], v[152:155], v[176:179], v[16:19]
	v_mfma_f32_16x16x32_bf16 v[4:7], v[144:147], v[184:187], v[4:7]
	v_mfma_f32_16x16x32_bf16 v[0:3], v[152:155], v[184:187], v[0:3]
	v_mfma_f32_16x16x32_bf16 v[52:55], v[148:151], v[164:167], v[52:55]
	v_mfma_f32_16x16x32_bf16 v[48:51], v[156:159], v[164:167], v[48:51]
	v_mfma_f32_16x16x32_bf16 v[36:39], v[148:151], v[172:175], v[36:39]
	v_mfma_f32_16x16x32_bf16 v[32:35], v[156:159], v[172:175], v[32:35]
	v_mfma_f32_16x16x32_bf16 v[20:23], v[148:151], v[180:183], v[20:23]
	v_mfma_f32_16x16x32_bf16 v[16:19], v[156:159], v[180:183], v[16:19]
	v_mfma_f32_16x16x32_bf16 v[4:7], v[148:151], v[188:191], v[4:7]
	v_mfma_f32_16x16x32_bf16 v[0:3], v[156:159], v[188:191], v[0:3]
	s_setprio 0
	s_barrier
	s_add_i32 s4, 0, 0x18000
	s_add_i32 s5, 0, 0x1c000
	v_add_u32_e32 v140, s4, v235
	v_add_u32_e32 v156, s5, v235
	ds_read_b128 v[128:131], v140
	ds_read_b128 v[132:135], v140 offset:1024
	ds_read_b128 v[136:139], v140 offset:2048
	ds_read_b128 v[140:143], v140 offset:3072
	ds_read_b128 v[144:147], v156
	ds_read_b128 v[148:151], v156 offset:1024
	ds_read_b128 v[152:155], v156 offset:2048
	ds_read_b128 v[156:159], v156 offset:3072
	s_add_u32 s14, s84, 0x4000
	s_addc_u32 s15, s85, 0
	s_mov_b32 m0, s70
	v_lshl_add_u64 v[216:217], s[14:15], 0, v[200:201]
	ds_read_b128 v[160:163], v237 offset:32768
	ds_read_b128 v[164:167], v237 offset:33792
	ds_read_b128 v[168:171], v237 offset:34816
	ds_read_b128 v[172:175], v237 offset:35840
	ds_read_b128 v[176:179], v237 offset:36864
	ds_read_b128 v[180:183], v237 offset:37888
	ds_read_b128 v[184:187], v237 offset:38912
	ds_read_b128 v[188:191], v237 offset:39936
	global_load_lds_dwordx4 v[216:217], off
	v_lshl_add_u64 v[216:217], s[14:15], 0, v[202:203]
	s_mov_b32 m0, s71
	s_nop 0
	global_load_lds_dwordx4 v[216:217], off
	s_waitcnt vmcnt(8)
	s_waitcnt lgkmcnt(0)
	s_setprio 1
	s_barrier
	v_mfma_f32_16x16x32_bf16 v[124:127], v[128:131], v[160:163], v[124:127]
	v_mfma_f32_16x16x32_bf16 v[120:123], v[136:139], v[160:163], v[120:123]
	v_mfma_f32_16x16x32_bf16 v[108:111], v[128:131], v[168:171], v[108:111]
	v_mfma_f32_16x16x32_bf16 v[104:107], v[136:139], v[168:171], v[104:107]
	v_mfma_f32_16x16x32_bf16 v[92:95], v[128:131], v[176:179], v[92:95]
	v_mfma_f32_16x16x32_bf16 v[88:91], v[136:139], v[176:179], v[88:91]
	v_mfma_f32_16x16x32_bf16 v[76:79], v[128:131], v[184:187], v[76:79]
	v_mfma_f32_16x16x32_bf16 v[72:75], v[136:139], v[184:187], v[72:75]
	v_mfma_f32_16x16x32_bf16 v[124:127], v[132:135], v[164:167], v[124:127]
	v_mfma_f32_16x16x32_bf16 v[120:123], v[140:143], v[164:167], v[120:123]
	v_mfma_f32_16x16x32_bf16 v[108:111], v[132:135], v[172:175], v[108:111]
	v_mfma_f32_16x16x32_bf16 v[104:107], v[140:143], v[172:175], v[104:107]
	v_mfma_f32_16x16x32_bf16 v[92:95], v[132:135], v[180:183], v[92:95]
	v_mfma_f32_16x16x32_bf16 v[88:91], v[140:143], v[180:183], v[88:91]
	v_mfma_f32_16x16x32_bf16 v[76:79], v[132:135], v[188:191], v[76:79]
	v_mfma_f32_16x16x32_bf16 v[72:75], v[140:143], v[188:191], v[72:75]
	s_setprio 0
	s_setprio 1
	v_mfma_f32_16x16x32_bf16 v[116:119], v[144:147], v[160:163], v[116:119]
	v_mfma_f32_16x16x32_bf16 v[112:115], v[152:155], v[160:163], v[112:115]
	v_mfma_f32_16x16x32_bf16 v[100:103], v[144:147], v[168:171], v[100:103]
	v_mfma_f32_16x16x32_bf16 v[96:99], v[152:155], v[168:171], v[96:99]
	v_mfma_f32_16x16x32_bf16 v[84:87], v[144:147], v[176:179], v[84:87]
	v_mfma_f32_16x16x32_bf16 v[80:83], v[152:155], v[176:179], v[80:83]
	v_mfma_f32_16x16x32_bf16 v[68:71], v[144:147], v[184:187], v[68:71]
	v_mfma_f32_16x16x32_bf16 v[64:67], v[152:155], v[184:187], v[64:67]
	v_mfma_f32_16x16x32_bf16 v[116:119], v[148:151], v[164:167], v[116:119]
	v_mfma_f32_16x16x32_bf16 v[112:115], v[156:159], v[164:167], v[112:115]
	v_mfma_f32_16x16x32_bf16 v[100:103], v[148:151], v[172:175], v[100:103]
	v_mfma_f32_16x16x32_bf16 v[96:99], v[156:159], v[172:175], v[96:99]
	v_mfma_f32_16x16x32_bf16 v[84:87], v[148:151], v[180:183], v[84:87]
	v_mfma_f32_16x16x32_bf16 v[80:83], v[156:159], v[180:183], v[80:83]
	v_mfma_f32_16x16x32_bf16 v[68:71], v[148:151], v[188:191], v[68:71]
	v_mfma_f32_16x16x32_bf16 v[64:67], v[156:159], v[188:191], v[64:67]
	s_setprio 0
	s_barrier
; #define PG8_STAGE(bufoff, gbase, voff) do { _Pragma("unroll") for (int _i = 0; _i < 2; ++_i) \
;         __builtin_amdgcn_global_load_lds((const unsigned*)((const char*)(gbase) + (voff)[_i]), (PG8_LAS unsigned*)(lds + (bufoff) + ldsw + _i * 8192), 16, 0, 0); } while (0)
; #define PG8_LDA(dst, b, h) do { _Pragma("unroll") for (int m = 0; m < 4; ++m) _Pragma("unroll") for (int k = 0; k < 2; ++k) dst[m][k] = *(const PG8_LAS bf16x8*)(lds + PG8_SA(b, h) + aoff + m * 2048 + k * 1024); } while (0)
; #define PG8_MMA(ai, bj, At, Bt) do { __builtin_amdgcn_s_setprio(1); _Pragma("unroll") for (int m = 0; m < 4; ++m) _Pragma("unroll") for (int n = 0; n < 2; ++n) _Pragma("unroll") for (int k = 0; k < 2; ++k) \
;         acc[ai][bj][m][n] = __builtin_amdgcn_mfma_f32_16x16x32_bf16(Bt[n][k], At[m][k], acc[ai][bj][m][n], 0, 0, 0); __builtin_amdgcn_s_setprio(0); } while (0)
; #define PG8_WAIT_V(n) asm volatile("s_waitcnt vmcnt(" #n ")" ::: "memory")
; #define PG8_WAIT_L(n) asm volatile("s_waitcnt lgkmcnt(" #n ")" ::: "memory")
; #define PG8_BAR __builtin_amdgcn_s_barrier()
; #define PG8_SCHED __builtin_amdgcn_sched_barrier(0)
; template <class Epi, class Sched, bool ALIGN_EPI = false, bool SP2 = true>
; __device__ __forceinline__ void gemm_phase(PG8_LAS unsigned char* lds, const Gemm g, const Sched& S, const Epi& E) {
;     ...
;         for (int t = 0; t < nt; t += 2) {
;     ...
;             PG8_LDA(At, 1, 1); PG8_STAGE(PG8_SB(1, 0), b3, voffB); PG8_STAGE(PG8_SB(1, 1), b3 + hstep, voffB); PG8_STAGE(PG8_SA(1, 0), a3, voffA);
;             PG8_WAIT_V(8); PG8_WAIT_L(0); PG8_BAR; PG8_MMA(1, 0, At, B0); PG8_MMA(1, 1, At, B1); PG8_BAR; PG8_SCHED;
	s_add_i32 s4, s4, s57
	v_lshl_add_u64 v[212:213], v[212:213], 0, s[18:19]
	s_mov_b32 m0, s4
	ds_read_b128 v[160:163], v237 offset:49152
	ds_read_b128 v[164:167], v237 offset:50176
	ds_read_b128 v[168:171], v237 offset:51200
	ds_read_b128 v[172:175], v237 offset:52224
	ds_read_b128 v[176:179], v237 offset:53248
	ds_read_b128 v[180:183], v237 offset:54272
	ds_read_b128 v[184:187], v237 offset:55296
	ds_read_b128 v[188:191], v237 offset:56320
	global_load_lds_dwordx4 v[212:213], off
	s_add_i32 m0, s4, 0x2000
	s_add_u32 s14, vcc_lo, 0xb0080
	v_lshl_add_u64 v[212:213], v[214:215], 0, s[18:19]
	s_addc_u32 s15, vcc_hi, 0
	s_add_i32 s4, s5, s57
	global_load_lds_dwordx4 v[212:213], off
	v_lshl_add_u64 v[212:213], s[14:15], 0, v[194:195]
	s_mov_b32 m0, s4
	s_nop 0
	global_load_lds_dwordx4 v[212:213], off
	v_lshl_add_u64 v[212:213], s[14:15], 0, v[204:205]
	s_add_i32 m0, s4, 0x2000
	s_nop 0
	global_load_lds_dwordx4 v[212:213], off
	v_lshl_add_u64 v[212:213], s[46:47], 0, v[200:201]
	s_mov_b32 m0, s34
	s_nop 0
	global_load_lds_dwordx4 v[212:213], off
	v_lshl_add_u64 v[212:213], s[46:47], 0, v[202:203]
	s_mov_b32 m0, s35
	s_nop 0
	global_load_lds_dwordx4 v[212:213], off
	s_waitcnt vmcnt(8)
	s_waitcnt lgkmcnt(0)
	s_setprio 1
	s_barrier
	v_mfma_f32_16x16x32_bf16 v[60:63], v[128:131], v[160:163], v[60:63]
	v_mfma_f32_16x16x32_bf16 v[56:59], v[136:139], v[160:163], v[56:59]
	v_mfma_f32_16x16x32_bf16 v[44:47], v[128:131], v[168:171], v[44:47]
	v_mfma_f32_16x16x32_bf16 v[40:43], v[136:139], v[168:171], v[40:43]
	v_mfma_f32_16x16x32_bf16 v[28:31], v[128:131], v[176:179], v[28:31]
	v_mfma_f32_16x16x32_bf16 v[24:27], v[136:139], v[176:179], v[24:27]
	v_mfma_f32_16x16x32_bf16 v[12:15], v[128:131], v[184:187], v[12:15]
	v_mfma_f32_16x16x32_bf16 v[8:11], v[136:139], v[184:187], v[8:11]
	v_mfma_f32_16x16x32_bf16 v[60:63], v[132:135], v[164:167], v[60:63]
	v_mfma_f32_16x16x32_bf16 v[56:59], v[140:143], v[164:167], v[56:59]
	v_mfma_f32_16x16x32_bf16 v[44:47], v[132:135], v[172:175], v[44:47]
	v_mfma_f32_16x16x32_bf16 v[40:43], v[140:143], v[172:175], v[40:43]
	v_mfma_f32_16x16x32_bf16 v[28:31], v[132:135], v[180:183], v[28:31]
	v_mfma_f32_16x16x32_bf16 v[24:27], v[140:143], v[180:183], v[24:27]
	v_mfma_f32_16x16x32_bf16 v[12:15], v[132:135], v[188:191], v[12:15]
	v_mfma_f32_16x16x32_bf16 v[8:11], v[140:143], v[188:191], v[8:11]
	s_setprio 0
	s_setprio 1
	v_mfma_f32_16x16x32_bf16 v[52:55], v[144:147], v[160:163], v[52:55]
	v_mfma_f32_16x16x32_bf16 v[48:51], v[152:155], v[160:163], v[48:51]
	v_mfma_f32_16x16x32_bf16 v[36:39], v[144:147], v[168:171], v[36:39]
	v_mfma_f32_16x16x32_bf16 v[32:35], v[152:155], v[168:171], v[32:35]
	v_mfma_f32_16x16x32_bf16 v[20:23], v[144:147], v[176:179], v[20:23]
	v_mfma_f32_16x16x32_bf16 v[16:19], v[152:155], v[176:179], v[16:19]
	v_mfma_f32_16x16x32_bf16 v[4:7], v[144:147], v[184:187], v[4:7]
	v_mfma_f32_16x16x32_bf16 v[0:3], v[152:155], v[184:187], v[0:3]
	v_mfma_f32_16x16x32_bf16 v[52:55], v[148:151], v[164:167], v[52:55]
	v_mfma_f32_16x16x32_bf16 v[48:51], v[156:159], v[164:167], v[48:51]
	v_mfma_f32_16x16x32_bf16 v[36:39], v[148:151], v[172:175], v[36:39]
	v_mfma_f32_16x16x32_bf16 v[32:35], v[156:159], v[172:175], v[32:35]
	v_mfma_f32_16x16x32_bf16 v[20:23], v[148:151], v[180:183], v[20:23]
	v_mfma_f32_16x16x32_bf16 v[16:19], v[156:159], v[180:183], v[16:19]
	v_mfma_f32_16x16x32_bf16 v[4:7], v[148:151], v[188:191], v[4:7]
	v_mfma_f32_16x16x32_bf16 v[0:3], v[156:159], v[188:191], v[0:3]
	s_setprio 0
	s_barrier
	s_add_i32 s7, s7, 2
	s_add_u32 s42, s42, 0x10000
	s_addc_u32 s43, s43, 0
	s_add_u32 s17, s17, 0x100
	s_addc_u32 s6, s6, 0
	s_cmp_gt_u32 s7, 41
	s_cbranch_scc0 .LBB0_236
	s_and_b64 vcc, exec, s[48:49]
	s_cbranch_vccz .LBB0_239
	s_barrier

; #define PG8_STAGE(bufoff, gbase, voff) do { _Pragma("unroll") for (int _i = 0; _i < 2; ++_i) \
;         __builtin_amdgcn_global_load_lds((const unsigned*)((const char*)(gbase) + (voff)[_i]), (PG8_LAS unsigned*)(lds + (bufoff) + ldsw + _i * 8192), 16, 0, 0); } while (0)
; #define PG8_LDA(dst, b, h) do { _Pragma("unroll") for (int m = 0; m < 4; ++m) _Pragma("unroll") for (int k = 0; k < 2; ++k) dst[m][k] = *(const PG8_LAS bf16x8*)(lds + PG8_SA(b, h) + aoff + m * 2048 + k * 1024); } while (0)
; #define PG8_LDB(dst, b, h) do { _Pragma("unroll") for (int n = 0; n < 2; ++n) _Pragma("unroll") for (int k = 0; k < 2; ++k) dst[n][k] = *(const PG8_LAS bf16x8*)(lds + PG8_SB(b, h) + boff + n * 2048 + k * 1024); } while (0)
; #define PG8_MMA(ai, bj, At, Bt) do { __builtin_amdgcn_s_setprio(1); _Pragma("unroll") for (int m = 0; m < 4; ++m) _Pragma("unroll") for (int n = 0; n < 2; ++n) _Pragma("unroll") for (int k = 0; k < 2; ++k) \
;         acc[ai][bj][m][n] = __builtin_amdgcn_mfma_f32_16x16x32_bf16(Bt[n][k], At[m][k], acc[ai][bj][m][n], 0, 0, 0); __builtin_amdgcn_s_setprio(0); } while (0)
; #define PG8_WAIT_V(n) asm volatile("s_waitcnt vmcnt(" #n ")" ::: "memory")
; #define PG8_WAIT_L(n) asm volatile("s_waitcnt lgkmcnt(" #n ")" ::: "memory")
; template <class Epi, class Sched, bool ALIGN_EPI = false, bool SP2 = true>
; __device__ __forceinline__ void gemm_phase(PG8_LAS unsigned char* lds, const Gemm g, const Sched& S, const Epi& E) {
;     ...
;             const bool last = (t == nt - 2);
;             const char* a1 = cA + (size_t)(t + 1) * kstepA;
;             const char* a2 = last ? nA : cA + (size_t)(t + 2) * kstepA; const char* b2 = last ? nB : cB + (size_t)(t + 2) * kstep;
;             const char* a3 = a2 + kstepA; const char* b3 = b2 + kstep;
;             if (last && has_next) S.a_ready(nxt);
;             if constexpr (SP2) {
;             PG8_LDB(B0, 0, 0); PG8_LDB(B1, 0, 1); PG8_SCHED; PG8_LDA(At, 0, 0); PG8_STAGE(PG8_SA(1, 1), a1 + hstepA, voffA);
;             PG8_WAIT_V(8); PG8_WAIT_L(0); PG8_BAR; PG8_MMA(0, 0, At, B0); PG8_MMA(0, 1, At, B1); PG8_BAR; PG8_SCHED;
;             PG8_LDA(At, 0, 1); PG8_STAGE(PG8_SB(0, 0), b2, voffB); PG8_STAGE(PG8_SB(0, 1), b2 + hstep, voffB); PG8_STAGE(PG8_SA(0, 0), a2, voffA);
;             PG8_WAIT_V(8); PG8_WAIT_L(0); PG8_BAR; PG8_MMA(1, 0, At, B0); PG8_MMA(1, 1, At, B1); PG8_BAR; PG8_SCHED;
.LBB0_376:
	s_add_u32 s4, s52, 0xfffc0080
	s_addc_u32 s5, s53, -1
	s_add_i32 s14, 0, 0x10000
	s_cmp_eq_u32 s59, 12
	s_cselect_b32 s85, s16, s5
	s_cselect_b32 s84, s17, s4
	v_add_u32_e32 v138, s14, v145
	s_cselect_b32 s47, s39, s7
	s_cselect_b32 s46, s41, s6
	s_add_i32 s4, 0, 0x14000
	ds_read_b128 v[150:153], v138
	ds_read_b128 v[154:157], v138 offset:1024
	ds_read_b128 v[158:161], v138 offset:2048
	ds_read_b128 v[162:165], v138 offset:3072
	v_add_u32_e32 v138, s4, v145
	ds_read_b128 v[166:169], v138
	ds_read_b128 v[170:173], v138 offset:1024
	ds_read_b128 v[174:177], v138 offset:2048
	ds_read_b128 v[178:181], v138 offset:3072
	v_lshl_add_u64 v[138:139], s[52:53], 0, v[134:135]
	s_add_i32 m0, s31, 0xc000
	ds_read_b128 v[182:185], v149
	ds_read_b128 v[186:189], v149 offset:1024
	ds_read_b128 v[200:203], v149 offset:2048
	ds_read_b128 v[204:207], v149 offset:3072
	ds_read_b128 v[208:211], v149 offset:4096
	ds_read_b128 v[212:215], v149 offset:5120
	ds_read_b128 v[216:219], v149 offset:6144
	ds_read_b128 v[220:223], v149 offset:7168
	global_load_lds_dwordx4 v[138:139], off
	v_lshl_add_u64 v[138:139], s[52:53], 0, v[136:137]
	s_add_i32 m0, s31, 0xe000
	s_nop 0
	global_load_lds_dwordx4 v[138:139], off
	s_waitcnt vmcnt(8)
	s_waitcnt lgkmcnt(0)
	s_setprio 1
	s_barrier
	v_mfma_f32_16x16x32_bf16 v[124:127], v[150:153], v[182:185], v[124:127]
	v_mfma_f32_16x16x32_bf16 v[120:123], v[158:161], v[182:185], v[120:123]
	v_mfma_f32_16x16x32_bf16 v[112:115], v[150:153], v[200:203], v[112:115]
	v_mfma_f32_16x16x32_bf16 v[104:107], v[158:161], v[200:203], v[104:107]
	v_mfma_f32_16x16x32_bf16 v[96:99], v[150:153], v[208:211], v[96:99]
	v_mfma_f32_16x16x32_bf16 v[88:91], v[158:161], v[208:211], v[88:91]
	v_mfma_f32_16x16x32_bf16 v[80:83], v[150:153], v[216:219], v[80:83]
	v_mfma_f32_16x16x32_bf16 v[72:75], v[158:161], v[216:219], v[72:75]
	v_mfma_f32_16x16x32_bf16 v[124:127], v[154:157], v[186:189], v[124:127]
	v_mfma_f32_16x16x32_bf16 v[120:123], v[162:165], v[186:189], v[120:123]
	v_mfma_f32_16x16x32_bf16 v[112:115], v[154:157], v[204:207], v[112:115]
	v_mfma_f32_16x16x32_bf16 v[104:107], v[162:165], v[204:207], v[104:107]
	v_mfma_f32_16x16x32_bf16 v[96:99], v[154:157], v[212:215], v[96:99]
	v_mfma_f32_16x16x32_bf16 v[88:91], v[162:165], v[212:215], v[88:91]
	v_mfma_f32_16x16x32_bf16 v[80:83], v[154:157], v[220:223], v[80:83]
	v_mfma_f32_16x16x32_bf16 v[72:75], v[162:165], v[220:223], v[72:75]
	s_setprio 0
	s_setprio 1
	v_mfma_f32_16x16x32_bf16 v[116:119], v[166:169], v[182:185], v[116:119]
	v_mfma_f32_16x16x32_bf16 v[108:111], v[174:177], v[182:185], v[108:111]
	v_mfma_f32_16x16x32_bf16 v[100:103], v[166:169], v[200:203], v[100:103]
	v_mfma_f32_16x16x32_bf16 v[92:95], v[174:177], v[200:203], v[92:95]
	v_mfma_f32_16x16x32_bf16 v[84:87], v[166:169], v[208:211], v[84:87]
	v_mfma_f32_16x16x32_bf16 v[76:79], v[174:177], v[208:211], v[76:79]
	v_mfma_f32_16x16x32_bf16 v[68:71], v[166:169], v[216:219], v[68:71]
	v_mfma_f32_16x16x32_bf16 v[64:67], v[174:177], v[216:219], v[64:67]
	v_mfma_f32_16x16x32_bf16 v[116:119], v[170:173], v[186:189], v[116:119]
	v_mfma_f32_16x16x32_bf16 v[108:111], v[178:181], v[186:189], v[108:111]
	v_mfma_f32_16x16x32_bf16 v[100:103], v[170:173], v[204:207], v[100:103]
	v_mfma_f32_16x16x32_bf16 v[92:95], v[178:181], v[204:207], v[92:95]
	v_mfma_f32_16x16x32_bf16 v[84:87], v[170:173], v[212:215], v[84:87]
	v_mfma_f32_16x16x32_bf16 v[76:79], v[178:181], v[212:215], v[76:79]
	v_mfma_f32_16x16x32_bf16 v[68:71], v[170:173], v[220:223], v[68:71]
	v_mfma_f32_16x16x32_bf16 v[64:67], v[178:181], v[220:223], v[64:67]
	s_setprio 0
	s_barrier
	s_add_i32 s5, s14, s28
	v_lshl_add_u64 v[138:139], s[46:47], 0, v[194:195]
	s_mov_b32 m0, s5
	ds_read_b128 v[182:185], v149 offset:16384
	ds_read_b128 v[186:189], v149 offset:17408
	ds_read_b128 v[200:203], v149 offset:18432
	ds_read_b128 v[204:207], v149 offset:19456
	ds_read_b128 v[208:211], v149 offset:20480
	ds_read_b128 v[212:215], v149 offset:21504
	ds_read_b128 v[216:219], v149 offset:22528
	ds_read_b128 v[220:223], v149 offset:23552
	global_load_lds_dwordx4 v[138:139], off
	s_add_i32 m0, s5, 0x2000
	s_add_u32 s14, s46, 0x40000
	v_lshl_add_u64 v[142:143], s[46:47], 0, v[128:129]
	s_addc_u32 s15, s47, 0
	s_add_i32 s4, s4, s28
	global_load_lds_dwordx4 v[142:143], off
	v_lshl_add_u64 v[190:191], s[14:15], 0, v[194:195]
	s_mov_b32 m0, s4
	v_lshl_add_u64 v[224:225], s[84:85], 0, v[130:131]
	global_load_lds_dwordx4 v[190:191], off
	v_lshl_add_u64 v[190:191], s[14:15], 0, v[128:129]
	s_add_i32 m0, s4, 0x2000
	s_nop 0
	global_load_lds_dwordx4 v[190:191], off
	v_lshl_add_u64 v[190:191], s[84:85], 0, v[132:133]
	s_mov_b32 m0, s31
	s_nop 0
	global_load_lds_dwordx4 v[190:191], off
	s_mov_b32 m0, s34
	s_nop 0
	global_load_lds_dwordx4 v[224:225], off
	s_waitcnt vmcnt(8)
	s_waitcnt lgkmcnt(0)
	s_setprio 1
	s_barrier
; #define PG8_STAGE(bufoff, gbase, voff) do { _Pragma("unroll") for (int _i = 0; _i < 2; ++_i) \
;         __builtin_amdgcn_global_load_lds((const unsigned*)((const char*)(gbase) + (voff)[_i]), (PG8_LAS unsigned*)(lds + (bufoff) + ldsw + _i * 8192), 16, 0, 0); } while (0)
; #define PG8_LDA(dst, b, h) do { _Pragma("unroll") for (int m = 0; m < 4; ++m) _Pragma("unroll") for (int k = 0; k < 2; ++k) dst[m][k] = *(const PG8_LAS bf16x8*)(lds + PG8_SA(b, h) + aoff + m * 2048 + k * 1024); } while (0)
; #define PG8_LDB(dst, b, h) do { _Pragma("unroll") for (int n = 0; n < 2; ++n) _Pragma("unroll") for (int k = 0; k < 2; ++k) dst[n][k] = *(const PG8_LAS bf16x8*)(lds + PG8_SB(b, h) + boff + n * 2048 + k * 1024); } while (0)
; #define PG8_MMA(ai, bj, At, Bt) do { __builtin_amdgcn_s_setprio(1); _Pragma("unroll") for (int m = 0; m < 4; ++m) _Pragma("unroll") for (int n = 0; n < 2; ++n) _Pragma("unroll") for (int k = 0; k < 2; ++k) \
;         acc[ai][bj][m][n] = __builtin_amdgcn_mfma_f32_16x16x32_bf16(Bt[n][k], At[m][k], acc[ai][bj][m][n], 0, 0, 0); __builtin_amdgcn_s_setprio(0); } while (0)
; #define PG8_WAIT_V(n) asm volatile("s_waitcnt vmcnt(" #n ")" ::: "memory")
; #define PG8_WAIT_L(n) asm volatile("s_waitcnt lgkmcnt(" #n ")" ::: "memory")
; #define PG8_BAR __builtin_amdgcn_s_barrier()
; #define PG8_SCHED __builtin_amdgcn_sched_barrier(0)
; template <class Epi, class Sched, bool ALIGN_EPI = false, bool SP2 = true>
; __device__ __forceinline__ void gemm_phase(PG8_LAS unsigned char* lds, const Gemm g, const Sched& S, const Epi& E) {
;     ...
;             PG8_WAIT_V(8); PG8_WAIT_L(0); PG8_BAR; PG8_MMA(1, 0, At, B0); PG8_MMA(1, 1, At, B1); PG8_BAR; PG8_SCHED;
;             PG8_LDB(B0, 1, 0); PG8_LDB(B1, 1, 1); PG8_SCHED; PG8_LDA(At, 1, 0); PG8_STAGE(PG8_SA(0, 1), a2 + hstepA, voffA);
;             PG8_WAIT_V(8); PG8_WAIT_L(0); PG8_BAR; PG8_MMA(0, 0, At, B0); PG8_MMA(0, 1, At, B1); PG8_BAR; PG8_SCHED;
;             PG8_LDA(At, 1, 1); PG8_STAGE(PG8_SB(1, 0), b3, voffB); PG8_STAGE(PG8_SB(1, 1), b3 + hstep, voffB); PG8_STAGE(PG8_SA(1, 0), a3, voffA);
	v_mfma_f32_16x16x32_bf16 v[60:63], v[150:153], v[182:185], v[60:63]
	v_mfma_f32_16x16x32_bf16 v[56:59], v[158:161], v[182:185], v[56:59]
	v_mfma_f32_16x16x32_bf16 v[48:51], v[150:153], v[200:203], v[48:51]
	v_mfma_f32_16x16x32_bf16 v[40:43], v[158:161], v[200:203], v[40:43]
	v_mfma_f32_16x16x32_bf16 v[32:35], v[150:153], v[208:211], v[32:35]
	v_mfma_f32_16x16x32_bf16 v[24:27], v[158:161], v[208:211], v[24:27]
	v_mfma_f32_16x16x32_bf16 v[16:19], v[150:153], v[216:219], v[16:19]
	v_mfma_f32_16x16x32_bf16 v[8:11], v[158:161], v[216:219], v[8:11]
	v_mfma_f32_16x16x32_bf16 v[60:63], v[154:157], v[186:189], v[60:63]
	v_mfma_f32_16x16x32_bf16 v[56:59], v[162:165], v[186:189], v[56:59]
	v_mfma_f32_16x16x32_bf16 v[48:51], v[154:157], v[204:207], v[48:51]
	v_mfma_f32_16x16x32_bf16 v[40:43], v[162:165], v[204:207], v[40:43]
	v_mfma_f32_16x16x32_bf16 v[32:35], v[154:157], v[212:215], v[32:35]
	v_mfma_f32_16x16x32_bf16 v[24:27], v[162:165], v[212:215], v[24:27]
	v_mfma_f32_16x16x32_bf16 v[16:19], v[154:157], v[220:223], v[16:19]
	v_mfma_f32_16x16x32_bf16 v[8:11], v[162:165], v[220:223], v[8:11]
	s_setprio 0
	s_setprio 1
	v_mfma_f32_16x16x32_bf16 v[52:55], v[166:169], v[182:185], v[52:55]
	v_mfma_f32_16x16x32_bf16 v[44:47], v[174:177], v[182:185], v[44:47]
	v_mfma_f32_16x16x32_bf16 v[36:39], v[166:169], v[200:203], v[36:39]
	v_mfma_f32_16x16x32_bf16 v[28:31], v[174:177], v[200:203], v[28:31]
	v_mfma_f32_16x16x32_bf16 v[20:23], v[166:169], v[208:211], v[20:23]
	v_mfma_f32_16x16x32_bf16 v[12:15], v[174:177], v[208:211], v[12:15]
	v_mfma_f32_16x16x32_bf16 v[4:7], v[166:169], v[216:219], v[4:7]
	v_mfma_f32_16x16x32_bf16 v[0:3], v[174:177], v[216:219], v[0:3]
	v_mfma_f32_16x16x32_bf16 v[52:55], v[170:173], v[186:189], v[52:55]
	v_mfma_f32_16x16x32_bf16 v[44:47], v[178:181], v[186:189], v[44:47]
	v_mfma_f32_16x16x32_bf16 v[36:39], v[170:173], v[204:207], v[36:39]
	v_mfma_f32_16x16x32_bf16 v[28:31], v[178:181], v[204:207], v[28:31]
	v_mfma_f32_16x16x32_bf16 v[20:23], v[170:173], v[212:215], v[20:23]
	v_mfma_f32_16x16x32_bf16 v[12:15], v[178:181], v[212:215], v[12:15]
	v_mfma_f32_16x16x32_bf16 v[4:7], v[170:173], v[220:223], v[4:7]
	v_mfma_f32_16x16x32_bf16 v[0:3], v[178:181], v[220:223], v[0:3]
	s_setprio 0
	s_barrier
	s_add_i32 s4, 0, 0x18000
	v_add_u32_e32 v140, s4, v145
	s_add_i32 s5, 0, 0x1c000
	ds_read_b128 v[150:153], v140
	ds_read_b128 v[154:157], v140 offset:1024
	ds_read_b128 v[158:161], v140 offset:2048
	ds_read_b128 v[162:165], v140 offset:3072
	v_add_u32_e32 v140, s5, v145
	ds_read_b128 v[166:169], v140
	ds_read_b128 v[170:173], v140 offset:1024
	ds_read_b128 v[174:177], v140 offset:2048
	ds_read_b128 v[178:181], v140 offset:3072
	s_add_u32 s14, s84, 0x40000
	s_addc_u32 s15, s85, 0
	s_mov_b32 m0, s35
	v_lshl_add_u64 v[226:227], s[14:15], 0, v[132:133]
	ds_read_b128 v[182:185], v149 offset:32768
	ds_read_b128 v[186:189], v149 offset:33792
	ds_read_b128 v[200:203], v149 offset:34816
	ds_read_b128 v[204:207], v149 offset:35840
	ds_read_b128 v[208:211], v149 offset:36864
	ds_read_b128 v[212:215], v149 offset:37888
	ds_read_b128 v[216:219], v149 offset:38912
	ds_read_b128 v[220:223], v149 offset:39936
	global_load_lds_dwordx4 v[226:227], off
	v_lshl_add_u64 v[226:227], s[14:15], 0, v[130:131]
	s_mov_b32 m0, s49
	s_nop 0
	global_load_lds_dwordx4 v[226:227], off
	s_waitcnt vmcnt(8)
	s_waitcnt lgkmcnt(0)
	s_setprio 1
	s_barrier
	v_mfma_f32_16x16x32_bf16 v[124:127], v[150:153], v[182:185], v[124:127]
	v_mfma_f32_16x16x32_bf16 v[120:123], v[158:161], v[182:185], v[120:123]
	v_mfma_f32_16x16x32_bf16 v[112:115], v[150:153], v[200:203], v[112:115]
	v_mfma_f32_16x16x32_bf16 v[104:107], v[158:161], v[200:203], v[104:107]
	v_mfma_f32_16x16x32_bf16 v[96:99], v[150:153], v[208:211], v[96:99]
	v_mfma_f32_16x16x32_bf16 v[88:91], v[158:161], v[208:211], v[88:91]
	v_mfma_f32_16x16x32_bf16 v[80:83], v[150:153], v[216:219], v[80:83]
	v_mfma_f32_16x16x32_bf16 v[72:75], v[158:161], v[216:219], v[72:75]
	v_mfma_f32_16x16x32_bf16 v[124:127], v[154:157], v[186:189], v[124:127]
	v_mfma_f32_16x16x32_bf16 v[120:123], v[162:165], v[186:189], v[120:123]
	v_mfma_f32_16x16x32_bf16 v[112:115], v[154:157], v[204:207], v[112:115]
	v_mfma_f32_16x16x32_bf16 v[104:107], v[162:165], v[204:207], v[104:107]
	v_mfma_f32_16x16x32_bf16 v[96:99], v[154:157], v[212:215], v[96:99]
	v_mfma_f32_16x16x32_bf16 v[88:91], v[162:165], v[212:215], v[88:91]
	v_mfma_f32_16x16x32_bf16 v[80:83], v[154:157], v[220:223], v[80:83]
	v_mfma_f32_16x16x32_bf16 v[72:75], v[162:165], v[220:223], v[72:75]
	s_setprio 0
	s_setprio 1
	v_mfma_f32_16x16x32_bf16 v[116:119], v[166:169], v[182:185], v[116:119]
	v_mfma_f32_16x16x32_bf16 v[108:111], v[174:177], v[182:185], v[108:111]
	v_mfma_f32_16x16x32_bf16 v[100:103], v[166:169], v[200:203], v[100:103]
	v_mfma_f32_16x16x32_bf16 v[92:95], v[174:177], v[200:203], v[92:95]
	v_mfma_f32_16x16x32_bf16 v[84:87], v[166:169], v[208:211], v[84:87]
	v_mfma_f32_16x16x32_bf16 v[76:79], v[174:177], v[208:211], v[76:79]
	v_mfma_f32_16x16x32_bf16 v[68:71], v[166:169], v[216:219], v[68:71]
	v_mfma_f32_16x16x32_bf16 v[64:67], v[174:177], v[216:219], v[64:67]
	v_mfma_f32_16x16x32_bf16 v[116:119], v[170:173], v[186:189], v[116:119]
	v_mfma_f32_16x16x32_bf16 v[108:111], v[178:181], v[186:189], v[108:111]
	v_mfma_f32_16x16x32_bf16 v[100:103], v[170:173], v[204:207], v[100:103]
	v_mfma_f32_16x16x32_bf16 v[92:95], v[178:181], v[204:207], v[92:95]
	v_mfma_f32_16x16x32_bf16 v[84:87], v[170:173], v[212:215], v[84:87]
	v_mfma_f32_16x16x32_bf16 v[76:79], v[178:181], v[212:215], v[76:79]
	v_mfma_f32_16x16x32_bf16 v[68:71], v[170:173], v[220:223], v[68:71]
	v_mfma_f32_16x16x32_bf16 v[64:67], v[178:181], v[220:223], v[64:67]
	s_setprio 0
	s_barrier
; #define PG8_STAGE(bufoff, gbase, voff) do { _Pragma("unroll") for (int _i = 0; _i < 2; ++_i) \
;         __builtin_amdgcn_global_load_lds((const unsigned*)((const char*)(gbase) + (voff)[_i]), (PG8_LAS unsigned*)(lds + (bufoff) + ldsw + _i * 8192), 16, 0, 0); } while (0)
; #define PG8_LDA(dst, b, h) do { _Pragma("unroll") for (int m = 0; m < 4; ++m) _Pragma("unroll") for (int k = 0; k < 2; ++k) dst[m][k] = *(const PG8_LAS bf16x8*)(lds + PG8_SA(b, h) + aoff + m * 2048 + k * 1024); } while (0)
; #define PG8_MMA(ai, bj, At, Bt) do { __builtin_amdgcn_s_setprio(1); _Pragma("unroll") for (int m = 0; m < 4; ++m) _Pragma("unroll") for (int n = 0; n < 2; ++n) _Pragma("unroll") for (int k = 0; k < 2; ++k) \
;         acc[ai][bj][m][n] = __builtin_amdgcn_mfma_f32_16x16x32_bf16(Bt[n][k], At[m][k], acc[ai][bj][m][n], 0, 0, 0); __builtin_amdgcn_s_setprio(0); } while (0)
; #define PG8_WAIT_V(n) asm volatile("s_waitcnt vmcnt(" #n ")" ::: "memory")
; #define PG8_WAIT_L(n) asm volatile("s_waitcnt lgkmcnt(" #n ")" ::: "memory")
; #define PG8_BAR __builtin_amdgcn_s_barrier()
; #define PG8_SCHED __builtin_amdgcn_sched_barrier(0)
; template <class Epi, class Sched, bool ALIGN_EPI = false, bool SP2 = true>
; __device__ __forceinline__ void gemm_phase(PG8_LAS unsigned char* lds, const Gemm g, const Sched& S, const Epi& E) {
;     ...
;         for (int t = 0; t < nt; t += 2) {
;     ...
;             PG8_LDA(At, 1, 1); PG8_STAGE(PG8_SB(1, 0), b3, voffB); PG8_STAGE(PG8_SB(1, 1), b3 + hstep, voffB); PG8_STAGE(PG8_SA(1, 0), a3, voffA);
;             PG8_WAIT_V(8); PG8_WAIT_L(0); PG8_BAR; PG8_MMA(1, 0, At, B0); PG8_MMA(1, 1, At, B1); PG8_BAR; PG8_SCHED;
	s_add_i32 s4, s4, s28
	v_lshl_add_u64 v[138:139], v[138:139], 0, s[18:19]
	s_mov_b32 m0, s4
	ds_read_b128 v[182:185], v149 offset:49152
	ds_read_b128 v[186:189], v149 offset:50176
	ds_read_b128 v[200:203], v149 offset:51200
	ds_read_b128 v[204:207], v149 offset:52224
	ds_read_b128 v[208:211], v149 offset:53248
	ds_read_b128 v[212:215], v149 offset:54272
	ds_read_b128 v[216:219], v149 offset:55296
	ds_read_b128 v[220:223], v149 offset:56320
	global_load_lds_dwordx4 v[138:139], off
	s_add_i32 m0, s4, 0x2000
	s_add_u32 s14, s46, 0x40080
	v_lshl_add_u64 v[138:139], v[142:143], 0, s[18:19]
	s_addc_u32 s15, s47, 0
	s_add_i32 s4, s5, s28
	global_load_lds_dwordx4 v[138:139], off
	v_lshl_add_u64 v[138:139], s[14:15], 0, v[194:195]
	s_mov_b32 m0, s4
	s_nop 0
	global_load_lds_dwordx4 v[138:139], off
	v_lshl_add_u64 v[138:139], s[14:15], 0, v[128:129]
	s_add_i32 m0, s4, 0x2000
	s_nop 0
	global_load_lds_dwordx4 v[138:139], off
	v_lshl_add_u64 v[138:139], v[190:191], 0, s[18:19]
	s_mov_b32 m0, s51
	s_nop 0
	global_load_lds_dwordx4 v[138:139], off
	v_lshl_add_u64 v[138:139], v[224:225], 0, s[18:19]
	s_mov_b32 m0, s57
	s_nop 0
	global_load_lds_dwordx4 v[138:139], off
	s_waitcnt vmcnt(8)
	s_waitcnt lgkmcnt(0)
	s_setprio 1
	s_barrier
	v_mfma_f32_16x16x32_bf16 v[60:63], v[150:153], v[182:185], v[60:63]
	v_mfma_f32_16x16x32_bf16 v[56:59], v[158:161], v[182:185], v[56:59]
	v_mfma_f32_16x16x32_bf16 v[48:51], v[150:153], v[200:203], v[48:51]
	v_mfma_f32_16x16x32_bf16 v[40:43], v[158:161], v[200:203], v[40:43]
	v_mfma_f32_16x16x32_bf16 v[32:35], v[150:153], v[208:211], v[32:35]
	v_mfma_f32_16x16x32_bf16 v[24:27], v[158:161], v[208:211], v[24:27]
	v_mfma_f32_16x16x32_bf16 v[16:19], v[150:153], v[216:219], v[16:19]
	v_mfma_f32_16x16x32_bf16 v[8:11], v[158:161], v[216:219], v[8:11]
	v_mfma_f32_16x16x32_bf16 v[60:63], v[154:157], v[186:189], v[60:63]
	v_mfma_f32_16x16x32_bf16 v[56:59], v[162:165], v[186:189], v[56:59]
	v_mfma_f32_16x16x32_bf16 v[48:51], v[154:157], v[204:207], v[48:51]
	v_mfma_f32_16x16x32_bf16 v[40:43], v[162:165], v[204:207], v[40:43]
	v_mfma_f32_16x16x32_bf16 v[32:35], v[154:157], v[212:215], v[32:35]
	v_mfma_f32_16x16x32_bf16 v[24:27], v[162:165], v[212:215], v[24:27]
	v_mfma_f32_16x16x32_bf16 v[16:19], v[154:157], v[220:223], v[16:19]
	v_mfma_f32_16x16x32_bf16 v[8:11], v[162:165], v[220:223], v[8:11]
	s_setprio 0
	s_setprio 1
	v_mfma_f32_16x16x32_bf16 v[52:55], v[166:169], v[182:185], v[52:55]
	v_mfma_f32_16x16x32_bf16 v[44:47], v[174:177], v[182:185], v[44:47]
	v_mfma_f32_16x16x32_bf16 v[36:39], v[166:169], v[200:203], v[36:39]
	v_mfma_f32_16x16x32_bf16 v[28:31], v[174:177], v[200:203], v[28:31]
	v_mfma_f32_16x16x32_bf16 v[20:23], v[166:169], v[208:211], v[20:23]
	v_mfma_f32_16x16x32_bf16 v[12:15], v[174:177], v[208:211], v[12:15]
	v_mfma_f32_16x16x32_bf16 v[4:7], v[166:169], v[216:219], v[4:7]
	v_mfma_f32_16x16x32_bf16 v[0:3], v[174:177], v[216:219], v[0:3]
	v_mfma_f32_16x16x32_bf16 v[52:55], v[170:173], v[186:189], v[52:55]
	v_mfma_f32_16x16x32_bf16 v[44:47], v[178:181], v[186:189], v[44:47]
	v_mfma_f32_16x16x32_bf16 v[36:39], v[170:173], v[204:207], v[36:39]
	v_mfma_f32_16x16x32_bf16 v[28:31], v[178:181], v[204:207], v[28:31]
	v_mfma_f32_16x16x32_bf16 v[20:23], v[170:173], v[212:215], v[20:23]
	v_mfma_f32_16x16x32_bf16 v[12:15], v[178:181], v[212:215], v[12:15]
	v_mfma_f32_16x16x32_bf16 v[4:7], v[170:173], v[220:223], v[4:7]
	v_mfma_f32_16x16x32_bf16 v[0:3], v[178:181], v[220:223], v[0:3]
	s_setprio 0
	s_barrier
	s_add_i32 s59, s59, 2
	s_add_u32 s52, s52, 0x100
	s_addc_u32 s53, s53, 0
	s_add_u32 s6, s6, 0x100
	s_addc_u32 s7, s7, 0
	s_cmp_gt_u32 s59, 13
	s_cbranch_scc0 .LBB0_376
	s_and_b64 vcc, exec, s[24:25]
	s_cbranch_vccz .LBB0_379
	s_barrier

; #define PG8_STAGE(bufoff, gbase, voff) do { _Pragma("unroll") for (int _i = 0; _i < 2; ++_i) \
;         __builtin_amdgcn_global_load_lds((const unsigned*)((const char*)(gbase) + (voff)[_i]), (PG8_LAS unsigned*)(lds + (bufoff) + ldsw + _i * 8192), 16, 0, 0); } while (0)
; #define PG8_LDA(dst, b, h) do { _Pragma("unroll") for (int m = 0; m < 4; ++m) _Pragma("unroll") for (int k = 0; k < 2; ++k) dst[m][k] = *(const PG8_LAS bf16x8*)(lds + PG8_SA(b, h) + aoff + m * 2048 + k * 1024); } while (0)
; #define PG8_LDB(dst, b, h) do { _Pragma("unroll") for (int n = 0; n < 2; ++n) _Pragma("unroll") for (int k = 0; k < 2; ++k) dst[n][k] = *(const PG8_LAS bf16x8*)(lds + PG8_SB(b, h) + boff + n * 2048 + k * 1024); } while (0)
; #define PG8_MMA(ai, bj, At, Bt) do { __builtin_amdgcn_s_setprio(1); _Pragma("unroll") for (int m = 0; m < 4; ++m) _Pragma("unroll") for (int n = 0; n < 2; ++n) _Pragma("unroll") for (int k = 0; k < 2; ++k) \
;         acc[ai][bj][m][n] = __builtin_amdgcn_mfma_f32_16x16x32_bf16(Bt[n][k], At[m][k], acc[ai][bj][m][n], 0, 0, 0); __builtin_amdgcn_s_setprio(0); } while (0)
; #define PG8_WAIT_V(n) asm volatile("s_waitcnt vmcnt(" #n ")" ::: "memory")
; #define PG8_BAR __builtin_amdgcn_s_barrier()
; template <class Epi, class Sched, bool ALIGN_EPI = false, bool SP2 = true>
; __device__ __forceinline__ void gemm_phase(PG8_LAS unsigned char* lds, const Gemm g, const Sched& S, const Epi& E) {
;     ...
;         for (int t = 0; t < nt; t += 2) {
;             const bool last = (t == nt - 2);
;             const char* a1 = cA + (size_t)(t + 1) * kstepA;
;             const char* a2 = last ? nA : cA + (size_t)(t + 2) * kstepA; const char* b2 = last ? nB : cB + (size_t)(t + 2) * kstep;
;             const char* a3 = a2 + kstepA; const char* b3 = b2 + kstep;
;             if (last && has_next) S.a_ready(nxt);
;             if constexpr (SP2) {
;             PG8_LDB(B0, 0, 0); PG8_LDB(B1, 0, 1); PG8_SCHED; PG8_LDA(At, 0, 0); PG8_STAGE(PG8_SA(1, 1), a1 + hstepA, voffA);
;             PG8_WAIT_V(8); PG8_WAIT_L(0); PG8_BAR; PG8_MMA(0, 0, At, B0); PG8_MMA(0, 1, At, B1); PG8_BAR; PG8_SCHED;
;             PG8_LDA(At, 0, 1); PG8_STAGE(PG8_SB(0, 0), b2, voffB); PG8_STAGE(PG8_SB(0, 1), b2 + hstep, voffB); PG8_STAGE(PG8_SA(0, 0), a2, voffA);
;             PG8_WAIT_V(8); PG8_WAIT_L(0); PG8_BAR; PG8_MMA(1, 0, At, B0); PG8_MMA(1, 1, At, B1); PG8_BAR; PG8_SCHED;
.LBB0_540:
	s_add_u32 s4, s44, s6
	s_addc_u32 s5, s45, 0
	s_add_u32 s7, s4, 0x100
	s_addc_u32 s50, s5, 0
	s_and_b64 s[14:15], s[48:49], exec
	s_cselect_b32 s53, s39, s50
	s_cselect_b32 s52, s38, s7
	s_add_u32 s6, s42, s6
	s_addc_u32 s7, s43, 0
	s_add_u32 s14, s6, 0x100
	s_addc_u32 s15, s7, 0
	s_add_i32 s71, 0, 0x10000
	s_and_b64 s[6:7], s[48:49], exec
	s_cselect_b32 s97, s21, s15
	s_cselect_b32 s96, s25, s14
	s_add_i32 s14, 0, 0x14000
	s_add_u32 s84, s4, 0x40080
	s_addc_u32 s85, s5, 0
	s_add_i32 s4, s71, s26
	s_add_i32 m0, s27, 0xc000
	s_add_i32 s5, s27, 0xe000
	s_add_i32 s59, s4, 0x2000
	v_add_u32_e32 v134, s71, v137
	s_add_u32 vcc_lo, s96, 0x10000
	ds_read_b128 v[140:143], v134
	ds_read_b128 v[144:147], v134 offset:1024
	ds_read_b128 v[148:151], v134 offset:2048
	ds_read_b128 v[152:155], v134 offset:3072
	v_add_u32_e32 v134, s14, v137
	s_addc_u32 vcc_hi, s97, 0
	s_add_i32 s70, s14, s26
	ds_read_b128 v[156:159], v134
	ds_read_b128 v[160:163], v134 offset:1024
	ds_read_b128 v[164:167], v134 offset:2048
	ds_read_b128 v[168:171], v134 offset:3072
	s_add_i32 s60, s70, 0x2000
	s_add_i32 s58, 0, 0x18000
	s_add_i32 s57, 0, 0x1c000
	s_add_u32 s50, s52, 0x40000
	s_addc_u32 s51, s53, 0
	s_add_i32 s7, s58, s26
	s_add_i32 s6, s7, 0x2000
	s_add_u32 s48, s96, 0x10080
	s_addc_u32 s49, s97, 0
	s_add_i32 s15, s57, s26
	s_add_i32 s14, s15, 0x2000
	v_lshl_add_u64 v[134:135], s[84:85], 0, v[132:133]
	ds_read_b128 v[172:175], v139
	ds_read_b128 v[176:179], v139 offset:1024
	ds_read_b128 v[180:183], v139 offset:2048
	ds_read_b128 v[184:187], v139 offset:3072
	ds_read_b128 v[188:191], v139 offset:4096
	ds_read_b128 v[200:203], v139 offset:5120
	ds_read_b128 v[204:207], v139 offset:6144
	ds_read_b128 v[208:211], v139 offset:7168
	global_load_lds_dwordx4 v[134:135], off
	v_lshl_add_u64 v[134:135], s[84:85], 0, v[130:131]
	s_mov_b32 m0, s5
	s_nop 0
	global_load_lds_dwordx4 v[134:135], off
	s_waitcnt vmcnt(8)
	s_waitcnt lgkmcnt(0)
	s_setprio 1
	s_barrier
	v_mfma_f32_16x16x32_bf16 v[124:127], v[140:143], v[172:175], v[124:127]
	v_mfma_f32_16x16x32_bf16 v[120:123], v[148:151], v[172:175], v[120:123]
	v_mfma_f32_16x16x32_bf16 v[116:119], v[140:143], v[180:183], v[116:119]
	v_mfma_f32_16x16x32_bf16 v[108:111], v[148:151], v[180:183], v[108:111]
	v_mfma_f32_16x16x32_bf16 v[100:103], v[140:143], v[188:191], v[100:103]
	v_mfma_f32_16x16x32_bf16 v[92:95], v[148:151], v[188:191], v[92:95]
	v_mfma_f32_16x16x32_bf16 v[80:83], v[140:143], v[204:207], v[80:83]
	v_mfma_f32_16x16x32_bf16 v[72:75], v[148:151], v[204:207], v[72:75]
	v_mfma_f32_16x16x32_bf16 v[124:127], v[144:147], v[176:179], v[124:127]
	v_mfma_f32_16x16x32_bf16 v[120:123], v[152:155], v[176:179], v[120:123]
	v_mfma_f32_16x16x32_bf16 v[116:119], v[144:147], v[184:187], v[116:119]
	v_mfma_f32_16x16x32_bf16 v[108:111], v[152:155], v[184:187], v[108:111]
	v_mfma_f32_16x16x32_bf16 v[100:103], v[144:147], v[200:203], v[100:103]
	v_mfma_f32_16x16x32_bf16 v[92:95], v[152:155], v[200:203], v[92:95]
	v_mfma_f32_16x16x32_bf16 v[80:83], v[144:147], v[208:211], v[80:83]
	v_mfma_f32_16x16x32_bf16 v[72:75], v[152:155], v[208:211], v[72:75]
	s_setprio 0
	s_setprio 1
	v_mfma_f32_16x16x32_bf16 v[112:115], v[156:159], v[172:175], v[112:115]
	v_mfma_f32_16x16x32_bf16 v[104:107], v[164:167], v[172:175], v[104:107]
	v_mfma_f32_16x16x32_bf16 v[96:99], v[156:159], v[180:183], v[96:99]
	v_mfma_f32_16x16x32_bf16 v[88:91], v[164:167], v[180:183], v[88:91]
	v_mfma_f32_16x16x32_bf16 v[84:87], v[156:159], v[188:191], v[84:87]
	v_mfma_f32_16x16x32_bf16 v[76:79], v[164:167], v[188:191], v[76:79]
	v_mfma_f32_16x16x32_bf16 v[68:71], v[156:159], v[204:207], v[68:71]
	v_mfma_f32_16x16x32_bf16 v[64:67], v[164:167], v[204:207], v[64:67]
	v_mfma_f32_16x16x32_bf16 v[112:115], v[160:163], v[176:179], v[112:115]
	v_mfma_f32_16x16x32_bf16 v[104:107], v[168:171], v[176:179], v[104:107]
	v_mfma_f32_16x16x32_bf16 v[96:99], v[160:163], v[184:187], v[96:99]
	v_mfma_f32_16x16x32_bf16 v[88:91], v[168:171], v[184:187], v[88:91]
	v_mfma_f32_16x16x32_bf16 v[84:87], v[160:163], v[200:203], v[84:87]
	v_mfma_f32_16x16x32_bf16 v[76:79], v[168:171], v[200:203], v[76:79]
	v_mfma_f32_16x16x32_bf16 v[68:71], v[160:163], v[208:211], v[68:71]
	v_mfma_f32_16x16x32_bf16 v[64:67], v[168:171], v[208:211], v[64:67]
	s_setprio 0
	s_barrier
	s_mov_b32 m0, s4
	v_lshl_add_u64 v[134:135], s[96:97], 0, v[194:195]
	ds_read_b128 v[172:175], v139 offset:16384
	ds_read_b128 v[176:179], v139 offset:17408
	ds_read_b128 v[180:183], v139 offset:18432
	ds_read_b128 v[184:187], v139 offset:19456
	ds_read_b128 v[188:191], v139 offset:20480
	ds_read_b128 v[200:203], v139 offset:21504
	ds_read_b128 v[204:207], v139 offset:22528
	ds_read_b128 v[208:211], v139 offset:23552
	global_load_lds_dwordx4 v[134:135], off
	v_lshl_add_u64 v[198:199], s[96:97], 0, v[128:129]
	s_mov_b32 m0, s59
	v_lshl_add_u64 v[212:213], vcc, 0, v[194:195]
	global_load_lds_dwordx4 v[198:199], off
	s_mov_b32 m0, s70
	v_lshl_add_u64 v[214:215], s[52:53], 0, v[130:131]
	global_load_lds_dwordx4 v[212:213], off
	v_lshl_add_u64 v[212:213], vcc, 0, v[128:129]
	s_mov_b32 m0, s60
	s_nop 0
	global_load_lds_dwordx4 v[212:213], off
	v_lshl_add_u64 v[212:213], s[52:53], 0, v[132:133]
	s_mov_b32 m0, s27
	s_nop 0
	global_load_lds_dwordx4 v[212:213], off
	s_mov_b32 m0, s28
	s_nop 0
	global_load_lds_dwordx4 v[214:215], off
	s_waitcnt vmcnt(8)
	s_waitcnt lgkmcnt(0)
	s_setprio 1
	s_barrier
; #define PG8_STAGE(bufoff, gbase, voff) do { _Pragma("unroll") for (int _i = 0; _i < 2; ++_i) \
;         __builtin_amdgcn_global_load_lds((const unsigned*)((const char*)(gbase) + (voff)[_i]), (PG8_LAS unsigned*)(lds + (bufoff) + ldsw + _i * 8192), 16, 0, 0); } while (0)
; #define PG8_LDA(dst, b, h) do { _Pragma("unroll") for (int m = 0; m < 4; ++m) _Pragma("unroll") for (int k = 0; k < 2; ++k) dst[m][k] = *(const PG8_LAS bf16x8*)(lds + PG8_SA(b, h) + aoff + m * 2048 + k * 1024); } while (0)
; #define PG8_LDB(dst, b, h) do { _Pragma("unroll") for (int n = 0; n < 2; ++n) _Pragma("unroll") for (int k = 0; k < 2; ++k) dst[n][k] = *(const PG8_LAS bf16x8*)(lds + PG8_SB(b, h) + boff + n * 2048 + k * 1024); } while (0)
; #define PG8_MMA(ai, bj, At, Bt) do { __builtin_amdgcn_s_setprio(1); _Pragma("unroll") for (int m = 0; m < 4; ++m) _Pragma("unroll") for (int n = 0; n < 2; ++n) _Pragma("unroll") for (int k = 0; k < 2; ++k) \
;         acc[ai][bj][m][n] = __builtin_amdgcn_mfma_f32_16x16x32_bf16(Bt[n][k], At[m][k], acc[ai][bj][m][n], 0, 0, 0); __builtin_amdgcn_s_setprio(0); } while (0)
; #define PG8_WAIT_V(n) asm volatile("s_waitcnt vmcnt(" #n ")" ::: "memory")
; #define PG8_WAIT_L(n) asm volatile("s_waitcnt lgkmcnt(" #n ")" ::: "memory")
; #define PG8_BAR __builtin_amdgcn_s_barrier()
; #define PG8_SCHED __builtin_amdgcn_sched_barrier(0)
; template <class Epi, class Sched, bool ALIGN_EPI = false, bool SP2 = true>
; __device__ __forceinline__ void gemm_phase(PG8_LAS unsigned char* lds, const Gemm g, const Sched& S, const Epi& E) {
;     ...
;             PG8_WAIT_V(8); PG8_WAIT_L(0); PG8_BAR; PG8_MMA(1, 0, At, B0); PG8_MMA(1, 1, At, B1); PG8_BAR; PG8_SCHED;
;             PG8_LDB(B0, 1, 0); PG8_LDB(B1, 1, 1); PG8_SCHED; PG8_LDA(At, 1, 0); PG8_STAGE(PG8_SA(0, 1), a2 + hstepA, voffA);
;             PG8_WAIT_V(8); PG8_WAIT_L(0); PG8_BAR; PG8_MMA(0, 0, At, B0); PG8_MMA(0, 1, At, B1); PG8_BAR; PG8_SCHED;
;             PG8_LDA(At, 1, 1); PG8_STAGE(PG8_SB(1, 0), b3, voffB); PG8_STAGE(PG8_SB(1, 1), b3 + hstep, voffB); PG8_STAGE(PG8_SA(1, 0), a3, voffA);
	v_mfma_f32_16x16x32_bf16 v[60:63], v[140:143], v[172:175], v[60:63]
	v_mfma_f32_16x16x32_bf16 v[56:59], v[148:151], v[172:175], v[56:59]
	v_mfma_f32_16x16x32_bf16 v[52:55], v[140:143], v[180:183], v[52:55]
	v_mfma_f32_16x16x32_bf16 v[44:47], v[148:151], v[180:183], v[44:47]
	v_mfma_f32_16x16x32_bf16 v[36:39], v[140:143], v[188:191], v[36:39]
	v_mfma_f32_16x16x32_bf16 v[28:31], v[148:151], v[188:191], v[28:31]
	v_mfma_f32_16x16x32_bf16 v[20:23], v[140:143], v[204:207], v[20:23]
	v_mfma_f32_16x16x32_bf16 v[12:15], v[148:151], v[204:207], v[12:15]
	v_mfma_f32_16x16x32_bf16 v[60:63], v[144:147], v[176:179], v[60:63]
	v_mfma_f32_16x16x32_bf16 v[56:59], v[152:155], v[176:179], v[56:59]
	v_mfma_f32_16x16x32_bf16 v[52:55], v[144:147], v[184:187], v[52:55]
	v_mfma_f32_16x16x32_bf16 v[44:47], v[152:155], v[184:187], v[44:47]
	v_mfma_f32_16x16x32_bf16 v[36:39], v[144:147], v[200:203], v[36:39]
	v_mfma_f32_16x16x32_bf16 v[28:31], v[152:155], v[200:203], v[28:31]
	v_mfma_f32_16x16x32_bf16 v[20:23], v[144:147], v[208:211], v[20:23]
	v_mfma_f32_16x16x32_bf16 v[12:15], v[152:155], v[208:211], v[12:15]
	s_setprio 0
	s_setprio 1
	v_mfma_f32_16x16x32_bf16 v[48:51], v[156:159], v[172:175], v[48:51]
	v_mfma_f32_16x16x32_bf16 v[40:43], v[164:167], v[172:175], v[40:43]
	v_mfma_f32_16x16x32_bf16 v[32:35], v[156:159], v[180:183], v[32:35]
	v_mfma_f32_16x16x32_bf16 v[24:27], v[164:167], v[180:183], v[24:27]
	v_mfma_f32_16x16x32_bf16 v[16:19], v[156:159], v[188:191], v[16:19]
	v_mfma_f32_16x16x32_bf16 v[8:11], v[164:167], v[188:191], v[8:11]
	v_mfma_f32_16x16x32_bf16 v[4:7], v[156:159], v[204:207], v[4:7]
	v_mfma_f32_16x16x32_bf16 v[0:3], v[164:167], v[204:207], v[0:3]
	v_mfma_f32_16x16x32_bf16 v[48:51], v[160:163], v[176:179], v[48:51]
	v_mfma_f32_16x16x32_bf16 v[40:43], v[168:171], v[176:179], v[40:43]
	v_mfma_f32_16x16x32_bf16 v[32:35], v[160:163], v[184:187], v[32:35]
	v_mfma_f32_16x16x32_bf16 v[24:27], v[168:171], v[184:187], v[24:27]
	v_mfma_f32_16x16x32_bf16 v[16:19], v[160:163], v[200:203], v[16:19]
	v_mfma_f32_16x16x32_bf16 v[8:11], v[168:171], v[200:203], v[8:11]
	v_mfma_f32_16x16x32_bf16 v[4:7], v[160:163], v[208:211], v[4:7]
	v_mfma_f32_16x16x32_bf16 v[0:3], v[168:171], v[208:211], v[0:3]
	s_setprio 0
	s_barrier
	v_add_u32_e32 v152, s58, v137
	v_add_u32_e32 v168, s57, v137
	ds_read_b128 v[140:143], v152
	ds_read_b128 v[144:147], v152 offset:1024
	ds_read_b128 v[148:151], v152 offset:2048
	ds_read_b128 v[152:155], v152 offset:3072
	ds_read_b128 v[156:159], v168
	ds_read_b128 v[160:163], v168 offset:1024
	ds_read_b128 v[164:167], v168 offset:2048
	ds_read_b128 v[168:171], v168 offset:3072
	s_mov_b32 m0, s29
	v_lshl_add_u64 v[216:217], s[50:51], 0, v[132:133]
	ds_read_b128 v[172:175], v139 offset:32768
	ds_read_b128 v[176:179], v139 offset:33792
	ds_read_b128 v[180:183], v139 offset:34816
	ds_read_b128 v[184:187], v139 offset:35840
	ds_read_b128 v[188:191], v139 offset:36864
	ds_read_b128 v[200:203], v139 offset:37888
	ds_read_b128 v[204:207], v139 offset:38912
	ds_read_b128 v[208:211], v139 offset:39936
	global_load_lds_dwordx4 v[216:217], off
	v_lshl_add_u64 v[216:217], s[50:51], 0, v[130:131]
	s_mov_b32 m0, s30
	s_nop 0
	global_load_lds_dwordx4 v[216:217], off
	s_waitcnt vmcnt(8)
	s_waitcnt lgkmcnt(0)
	s_setprio 1
	s_barrier
	v_mfma_f32_16x16x32_bf16 v[124:127], v[140:143], v[172:175], v[124:127]
	v_mfma_f32_16x16x32_bf16 v[120:123], v[148:151], v[172:175], v[120:123]
	v_mfma_f32_16x16x32_bf16 v[116:119], v[140:143], v[180:183], v[116:119]
	v_mfma_f32_16x16x32_bf16 v[108:111], v[148:151], v[180:183], v[108:111]
	v_mfma_f32_16x16x32_bf16 v[100:103], v[140:143], v[188:191], v[100:103]
	v_mfma_f32_16x16x32_bf16 v[92:95], v[148:151], v[188:191], v[92:95]
	v_mfma_f32_16x16x32_bf16 v[80:83], v[140:143], v[204:207], v[80:83]
	v_mfma_f32_16x16x32_bf16 v[72:75], v[148:151], v[204:207], v[72:75]
	v_mfma_f32_16x16x32_bf16 v[124:127], v[144:147], v[176:179], v[124:127]
	v_mfma_f32_16x16x32_bf16 v[120:123], v[152:155], v[176:179], v[120:123]
	v_mfma_f32_16x16x32_bf16 v[116:119], v[144:147], v[184:187], v[116:119]
	v_mfma_f32_16x16x32_bf16 v[108:111], v[152:155], v[184:187], v[108:111]
	v_mfma_f32_16x16x32_bf16 v[100:103], v[144:147], v[200:203], v[100:103]
	v_mfma_f32_16x16x32_bf16 v[92:95], v[152:155], v[200:203], v[92:95]
	v_mfma_f32_16x16x32_bf16 v[80:83], v[144:147], v[208:211], v[80:83]
	v_mfma_f32_16x16x32_bf16 v[72:75], v[152:155], v[208:211], v[72:75]
	s_setprio 0
	s_setprio 1
	v_mfma_f32_16x16x32_bf16 v[112:115], v[156:159], v[172:175], v[112:115]
	v_mfma_f32_16x16x32_bf16 v[104:107], v[164:167], v[172:175], v[104:107]
	v_mfma_f32_16x16x32_bf16 v[96:99], v[156:159], v[180:183], v[96:99]
	v_mfma_f32_16x16x32_bf16 v[88:91], v[164:167], v[180:183], v[88:91]
	v_mfma_f32_16x16x32_bf16 v[84:87], v[156:159], v[188:191], v[84:87]
	v_mfma_f32_16x16x32_bf16 v[76:79], v[164:167], v[188:191], v[76:79]
	v_mfma_f32_16x16x32_bf16 v[68:71], v[156:159], v[204:207], v[68:71]
	v_mfma_f32_16x16x32_bf16 v[64:67], v[164:167], v[204:207], v[64:67]
	v_mfma_f32_16x16x32_bf16 v[112:115], v[160:163], v[176:179], v[112:115]
	v_mfma_f32_16x16x32_bf16 v[104:107], v[168:171], v[176:179], v[104:107]
	v_mfma_f32_16x16x32_bf16 v[96:99], v[160:163], v[184:187], v[96:99]
	v_mfma_f32_16x16x32_bf16 v[88:91], v[168:171], v[184:187], v[88:91]
	v_mfma_f32_16x16x32_bf16 v[84:87], v[160:163], v[200:203], v[84:87]
	v_mfma_f32_16x16x32_bf16 v[76:79], v[168:171], v[200:203], v[76:79]
	v_mfma_f32_16x16x32_bf16 v[68:71], v[160:163], v[208:211], v[68:71]
	v_mfma_f32_16x16x32_bf16 v[64:67], v[168:171], v[208:211], v[64:67]
	s_setprio 0
	s_barrier
; #define PG8_STAGE(bufoff, gbase, voff) do { _Pragma("unroll") for (int _i = 0; _i < 2; ++_i) \
;         __builtin_amdgcn_global_load_lds((const unsigned*)((const char*)(gbase) + (voff)[_i]), (PG8_LAS unsigned*)(lds + (bufoff) + ldsw + _i * 8192), 16, 0, 0); } while (0)
; #define PG8_LDA(dst, b, h) do { _Pragma("unroll") for (int m = 0; m < 4; ++m) _Pragma("unroll") for (int k = 0; k < 2; ++k) dst[m][k] = *(const PG8_LAS bf16x8*)(lds + PG8_SA(b, h) + aoff + m * 2048 + k * 1024); } while (0)
; #define PG8_MMA(ai, bj, At, Bt) do { __builtin_amdgcn_s_setprio(1); _Pragma("unroll") for (int m = 0; m < 4; ++m) _Pragma("unroll") for (int n = 0; n < 2; ++n) _Pragma("unroll") for (int k = 0; k < 2; ++k) \
;         acc[ai][bj][m][n] = __builtin_amdgcn_mfma_f32_16x16x32_bf16(Bt[n][k], At[m][k], acc[ai][bj][m][n], 0, 0, 0); __builtin_amdgcn_s_setprio(0); } while (0)
; #define PG8_WAIT_V(n) asm volatile("s_waitcnt vmcnt(" #n ")" ::: "memory")
; #define PG8_WAIT_L(n) asm volatile("s_waitcnt lgkmcnt(" #n ")" ::: "memory")
; #define PG8_BAR __builtin_amdgcn_s_barrier()
; #define PG8_SCHED __builtin_amdgcn_sched_barrier(0)
; template <class Epi, class Sched, bool ALIGN_EPI = false, bool SP2 = true>
; __device__ __forceinline__ void gemm_phase(PG8_LAS unsigned char* lds, const Gemm g, const Sched& S, const Epi& E) {
;     ...
;         for (int t = 0; t < nt; t += 2) {
;     ...
;             PG8_LDA(At, 1, 1); PG8_STAGE(PG8_SB(1, 0), b3, voffB); PG8_STAGE(PG8_SB(1, 1), b3 + hstep, voffB); PG8_STAGE(PG8_SA(1, 0), a3, voffA);
;             PG8_WAIT_V(8); PG8_WAIT_L(0); PG8_BAR; PG8_MMA(1, 0, At, B0); PG8_MMA(1, 1, At, B1); PG8_BAR; PG8_SCHED;
	s_mov_b32 m0, s7
	v_lshl_add_u64 v[134:135], v[134:135], 0, s[18:19]
	ds_read_b128 v[172:175], v139 offset:49152
	ds_read_b128 v[176:179], v139 offset:50176
	ds_read_b128 v[180:183], v139 offset:51200
	ds_read_b128 v[184:187], v139 offset:52224
	ds_read_b128 v[188:191], v139 offset:53248
	ds_read_b128 v[200:203], v139 offset:54272
	ds_read_b128 v[204:207], v139 offset:55296
	ds_read_b128 v[208:211], v139 offset:56320
	global_load_lds_dwordx4 v[134:135], off
	v_lshl_add_u64 v[134:135], v[198:199], 0, s[18:19]
	s_mov_b32 m0, s6
	s_nop 0
	global_load_lds_dwordx4 v[134:135], off
	v_lshl_add_u64 v[134:135], s[48:49], 0, v[194:195]
	s_mov_b32 m0, s15
	s_nop 0
	global_load_lds_dwordx4 v[134:135], off
	v_lshl_add_u64 v[134:135], s[48:49], 0, v[128:129]
	s_mov_b32 m0, s14
	s_nop 0
	global_load_lds_dwordx4 v[134:135], off
	v_lshl_add_u64 v[134:135], v[212:213], 0, s[18:19]
	s_mov_b32 m0, s31
	s_nop 0
	global_load_lds_dwordx4 v[134:135], off
	v_lshl_add_u64 v[134:135], v[214:215], 0, s[18:19]
	s_mov_b32 m0, s34
	s_nop 0
	global_load_lds_dwordx4 v[134:135], off
	s_waitcnt vmcnt(8)
	s_waitcnt lgkmcnt(0)
	s_setprio 1
	s_barrier
	v_mfma_f32_16x16x32_bf16 v[60:63], v[140:143], v[172:175], v[60:63]
	v_mfma_f32_16x16x32_bf16 v[56:59], v[148:151], v[172:175], v[56:59]
	v_mfma_f32_16x16x32_bf16 v[52:55], v[140:143], v[180:183], v[52:55]
	v_mfma_f32_16x16x32_bf16 v[44:47], v[148:151], v[180:183], v[44:47]
	v_mfma_f32_16x16x32_bf16 v[36:39], v[140:143], v[188:191], v[36:39]
	v_mfma_f32_16x16x32_bf16 v[28:31], v[148:151], v[188:191], v[28:31]
	v_mfma_f32_16x16x32_bf16 v[20:23], v[140:143], v[204:207], v[20:23]
	v_mfma_f32_16x16x32_bf16 v[12:15], v[148:151], v[204:207], v[12:15]
	v_mfma_f32_16x16x32_bf16 v[60:63], v[144:147], v[176:179], v[60:63]
	v_mfma_f32_16x16x32_bf16 v[56:59], v[152:155], v[176:179], v[56:59]
	v_mfma_f32_16x16x32_bf16 v[52:55], v[144:147], v[184:187], v[52:55]
	v_mfma_f32_16x16x32_bf16 v[44:47], v[152:155], v[184:187], v[44:47]
	v_mfma_f32_16x16x32_bf16 v[36:39], v[144:147], v[200:203], v[36:39]
	v_mfma_f32_16x16x32_bf16 v[28:31], v[152:155], v[200:203], v[28:31]
	v_mfma_f32_16x16x32_bf16 v[20:23], v[144:147], v[208:211], v[20:23]
	v_mfma_f32_16x16x32_bf16 v[12:15], v[152:155], v[208:211], v[12:15]
	s_setprio 0
	s_setprio 1
	v_mfma_f32_16x16x32_bf16 v[48:51], v[156:159], v[172:175], v[48:51]
	v_mfma_f32_16x16x32_bf16 v[40:43], v[164:167], v[172:175], v[40:43]
	v_mfma_f32_16x16x32_bf16 v[32:35], v[156:159], v[180:183], v[32:35]
	v_mfma_f32_16x16x32_bf16 v[24:27], v[164:167], v[180:183], v[24:27]
	v_mfma_f32_16x16x32_bf16 v[16:19], v[156:159], v[188:191], v[16:19]
	v_mfma_f32_16x16x32_bf16 v[8:11], v[164:167], v[188:191], v[8:11]
	v_mfma_f32_16x16x32_bf16 v[4:7], v[156:159], v[204:207], v[4:7]
	v_mfma_f32_16x16x32_bf16 v[0:3], v[164:167], v[204:207], v[0:3]
	v_mfma_f32_16x16x32_bf16 v[48:51], v[160:163], v[176:179], v[48:51]
	v_mfma_f32_16x16x32_bf16 v[40:43], v[168:171], v[176:179], v[40:43]
	v_mfma_f32_16x16x32_bf16 v[32:35], v[160:163], v[184:187], v[32:35]
	v_mfma_f32_16x16x32_bf16 v[24:27], v[168:171], v[184:187], v[24:27]
	v_mfma_f32_16x16x32_bf16 v[16:19], v[160:163], v[200:203], v[16:19]
	v_mfma_f32_16x16x32_bf16 v[8:11], v[168:171], v[200:203], v[8:11]
	v_mfma_f32_16x16x32_bf16 v[4:7], v[160:163], v[208:211], v[4:7]
	v_mfma_f32_16x16x32_bf16 v[0:3], v[168:171], v[208:211], v[0:3]
	s_setprio 0
	s_barrier
	s_movk_i32 s6, 0x100
	s_andn2_b64 vcc, exec, s[46:47]
	s_mov_b64 s[48:49], -1
	s_mov_b64 s[46:47], 0
	s_cbranch_vccz .LBB0_540
	s_and_b64 vcc, exec, s[10:11]
	s_cbranch_vccz .LBB0_543
	s_barrier

; #define PG8_STAGE(bufoff, gbase, voff) do { _Pragma("unroll") for (int _i = 0; _i < 2; ++_i) \
;         __builtin_amdgcn_global_load_lds((const unsigned*)((const char*)(gbase) + (voff)[_i]), (PG8_LAS unsigned*)(lds + (bufoff) + ldsw + _i * 8192), 16, 0, 0); } while (0)
; #define PG8_LDA(dst, b, h) do { _Pragma("unroll") for (int m = 0; m < 4; ++m) _Pragma("unroll") for (int k = 0; k < 2; ++k) dst[m][k] = *(const PG8_LAS bf16x8*)(lds + PG8_SA(b, h) + aoff + m * 2048 + k * 1024); } while (0)
; #define PG8_LDB(dst, b, h) do { _Pragma("unroll") for (int n = 0; n < 2; ++n) _Pragma("unroll") for (int k = 0; k < 2; ++k) dst[n][k] = *(const PG8_LAS bf16x8*)(lds + PG8_SB(b, h) + boff + n * 2048 + k * 1024); } while (0)
; #define PG8_MMA(ai, bj, At, Bt) do { __builtin_amdgcn_s_setprio(1); _Pragma("unroll") for (int m = 0; m < 4; ++m) _Pragma("unroll") for (int n = 0; n < 2; ++n) _Pragma("unroll") for (int k = 0; k < 2; ++k) \
;         acc[ai][bj][m][n] = __builtin_amdgcn_mfma_f32_16x16x32_bf16(Bt[n][k], At[m][k], acc[ai][bj][m][n], 0, 0, 0); __builtin_amdgcn_s_setprio(0); } while (0)
; #define PG8_WAIT_V(n) asm volatile("s_waitcnt vmcnt(" #n ")" ::: "memory")
; #define PG8_WAIT_L(n) asm volatile("s_waitcnt lgkmcnt(" #n ")" ::: "memory")
; template <class Epi, class Sched, bool ALIGN_EPI = false, bool SP2 = true>
; __device__ __forceinline__ void gemm_phase(PG8_LAS unsigned char* lds, const Gemm g, const Sched& S, const Epi& E) {
;     ...
;             const bool last = (t == nt - 2);
;             const char* a1 = cA + (size_t)(t + 1) * kstepA;
;             const char* a2 = last ? nA : cA + (size_t)(t + 2) * kstepA; const char* b2 = last ? nB : cB + (size_t)(t + 2) * kstep;
;             const char* a3 = a2 + kstepA; const char* b3 = b2 + kstep;
;             if (last && has_next) S.a_ready(nxt);
;             if constexpr (SP2) {
;             PG8_LDB(B0, 0, 0); PG8_LDB(B1, 0, 1); PG8_SCHED; PG8_LDA(At, 0, 0); PG8_STAGE(PG8_SA(1, 1), a1 + hstepA, voffA);
;             PG8_WAIT_V(8); PG8_WAIT_L(0); PG8_BAR; PG8_MMA(0, 0, At, B0); PG8_MMA(0, 1, At, B1); PG8_BAR; PG8_SCHED;
;             PG8_LDA(At, 0, 1); PG8_STAGE(PG8_SB(0, 0), b2, voffB); PG8_STAGE(PG8_SB(0, 1), b2 + hstep, voffB); PG8_STAGE(PG8_SA(0, 0), a2, voffA);
;             PG8_WAIT_V(8); PG8_WAIT_L(0); PG8_BAR; PG8_MMA(1, 0, At, B0); PG8_MMA(1, 1, At, B1); PG8_BAR; PG8_SCHED;
.LBB0_745:
	s_add_u32 s4, s50, 0xfffc0080
	s_addc_u32 s5, s51, -1
	s_add_i32 s14, 0, 0x10000
	s_cmp_eq_u32 s47, 12
	s_cselect_b32 s85, s16, s5
	s_cselect_b32 s84, s17, s4
	s_cselect_b32 s53, s25, s7
	s_cselect_b32 s52, s41, s6
	s_add_i32 s4, 0, 0x14000
	v_add_u32_e32 v146, s14, v173
	v_add_u32_e32 v162, s4, v173
	ds_read_b128 v[134:137], v146
	ds_read_b128 v[138:141], v146 offset:1024
	ds_read_b128 v[142:145], v146 offset:2048
	ds_read_b128 v[146:149], v146 offset:3072
	ds_read_b128 v[150:153], v162
	ds_read_b128 v[154:157], v162 offset:1024
	ds_read_b128 v[158:161], v162 offset:2048
	ds_read_b128 v[162:165], v162 offset:3072
	v_lshl_add_u64 v[170:171], s[50:51], 0, v[130:131]
	s_add_i32 m0, s31, 0xc000
	ds_read_b128 v[166:169], v175
	ds_read_b128 v[176:179], v175 offset:1024
	ds_read_b128 v[180:183], v175 offset:2048
	ds_read_b128 v[184:187], v175 offset:3072
	ds_read_b128 v[188:191], v175 offset:4096
	ds_read_b128 v[200:203], v175 offset:5120
	ds_read_b128 v[204:207], v175 offset:6144
	ds_read_b128 v[208:211], v175 offset:7168
	global_load_lds_dwordx4 v[170:171], off
	v_lshl_add_u64 v[170:171], s[50:51], 0, v[132:133]
	s_add_i32 m0, s31, 0xe000
	s_nop 0
	global_load_lds_dwordx4 v[170:171], off
	s_waitcnt vmcnt(8)
	s_waitcnt lgkmcnt(0)
	s_setprio 1
	s_barrier
	v_mfma_f32_16x16x32_bf16 v[124:127], v[134:137], v[166:169], v[124:127]
	v_mfma_f32_16x16x32_bf16 v[120:123], v[142:145], v[166:169], v[120:123]
	v_mfma_f32_16x16x32_bf16 v[108:111], v[134:137], v[180:183], v[108:111]
	v_mfma_f32_16x16x32_bf16 v[104:107], v[142:145], v[180:183], v[104:107]
	v_mfma_f32_16x16x32_bf16 v[92:95], v[134:137], v[188:191], v[92:95]
	v_mfma_f32_16x16x32_bf16 v[88:91], v[142:145], v[188:191], v[88:91]
	v_mfma_f32_16x16x32_bf16 v[76:79], v[134:137], v[204:207], v[76:79]
	v_mfma_f32_16x16x32_bf16 v[72:75], v[142:145], v[204:207], v[72:75]
	v_mfma_f32_16x16x32_bf16 v[124:127], v[138:141], v[176:179], v[124:127]
	v_mfma_f32_16x16x32_bf16 v[120:123], v[146:149], v[176:179], v[120:123]
	v_mfma_f32_16x16x32_bf16 v[108:111], v[138:141], v[184:187], v[108:111]
	v_mfma_f32_16x16x32_bf16 v[104:107], v[146:149], v[184:187], v[104:107]
	v_mfma_f32_16x16x32_bf16 v[92:95], v[138:141], v[200:203], v[92:95]
	v_mfma_f32_16x16x32_bf16 v[88:91], v[146:149], v[200:203], v[88:91]
	v_mfma_f32_16x16x32_bf16 v[76:79], v[138:141], v[208:211], v[76:79]
	v_mfma_f32_16x16x32_bf16 v[72:75], v[146:149], v[208:211], v[72:75]
	s_setprio 0
	s_setprio 1
	v_mfma_f32_16x16x32_bf16 v[116:119], v[150:153], v[166:169], v[116:119]
	v_mfma_f32_16x16x32_bf16 v[112:115], v[158:161], v[166:169], v[112:115]
	v_mfma_f32_16x16x32_bf16 v[100:103], v[150:153], v[180:183], v[100:103]
	v_mfma_f32_16x16x32_bf16 v[96:99], v[158:161], v[180:183], v[96:99]
	v_mfma_f32_16x16x32_bf16 v[84:87], v[150:153], v[188:191], v[84:87]
	v_mfma_f32_16x16x32_bf16 v[80:83], v[158:161], v[188:191], v[80:83]
	v_mfma_f32_16x16x32_bf16 v[68:71], v[150:153], v[204:207], v[68:71]
	v_mfma_f32_16x16x32_bf16 v[64:67], v[158:161], v[204:207], v[64:67]
	v_mfma_f32_16x16x32_bf16 v[116:119], v[154:157], v[176:179], v[116:119]
	v_mfma_f32_16x16x32_bf16 v[112:115], v[162:165], v[176:179], v[112:115]
	v_mfma_f32_16x16x32_bf16 v[100:103], v[154:157], v[184:187], v[100:103]
	v_mfma_f32_16x16x32_bf16 v[96:99], v[162:165], v[184:187], v[96:99]
	v_mfma_f32_16x16x32_bf16 v[84:87], v[154:157], v[200:203], v[84:87]
	v_mfma_f32_16x16x32_bf16 v[80:83], v[162:165], v[200:203], v[80:83]
	v_mfma_f32_16x16x32_bf16 v[68:71], v[154:157], v[208:211], v[68:71]
	v_mfma_f32_16x16x32_bf16 v[64:67], v[162:165], v[208:211], v[64:67]
	s_setprio 0
	s_barrier
	s_add_i32 s5, s14, s30
	v_lshl_add_u64 v[170:171], s[52:53], 0, v[194:195]
	s_mov_b32 m0, s5
	ds_read_b128 v[166:169], v175 offset:16384
	ds_read_b128 v[176:179], v175 offset:17408
	ds_read_b128 v[180:183], v175 offset:18432
	ds_read_b128 v[184:187], v175 offset:19456
	ds_read_b128 v[188:191], v175 offset:20480
	ds_read_b128 v[200:203], v175 offset:21504
	ds_read_b128 v[204:207], v175 offset:22528
	ds_read_b128 v[208:211], v175 offset:23552
	global_load_lds_dwordx4 v[170:171], off
	s_add_i32 m0, s5, 0x2000
	s_add_u32 s14, s52, 0x40000
	v_lshl_add_u64 v[198:199], s[52:53], 0, v[128:129]
	s_addc_u32 s15, s53, 0
	s_add_i32 s4, s4, s30
	global_load_lds_dwordx4 v[198:199], off
	v_lshl_add_u64 v[212:213], s[14:15], 0, v[194:195]
	s_mov_b32 m0, s4
	v_lshl_add_u64 v[214:215], s[84:85], 0, v[128:129]
	global_load_lds_dwordx4 v[212:213], off
	v_lshl_add_u64 v[212:213], s[14:15], 0, v[128:129]
	s_add_i32 m0, s4, 0x2000
	s_nop 0
	global_load_lds_dwordx4 v[212:213], off
	v_lshl_add_u64 v[212:213], s[84:85], 0, v[194:195]
	s_mov_b32 m0, s31
	s_nop 0
	global_load_lds_dwordx4 v[212:213], off
	s_mov_b32 m0, s34
	s_nop 0
	global_load_lds_dwordx4 v[214:215], off
	s_waitcnt vmcnt(8)
	s_waitcnt lgkmcnt(0)
	s_setprio 1
	s_barrier
; #define PG8_STAGE(bufoff, gbase, voff) do { _Pragma("unroll") for (int _i = 0; _i < 2; ++_i) \
;         __builtin_amdgcn_global_load_lds((const unsigned*)((const char*)(gbase) + (voff)[_i]), (PG8_LAS unsigned*)(lds + (bufoff) + ldsw + _i * 8192), 16, 0, 0); } while (0)
; #define PG8_LDA(dst, b, h) do { _Pragma("unroll") for (int m = 0; m < 4; ++m) _Pragma("unroll") for (int k = 0; k < 2; ++k) dst[m][k] = *(const PG8_LAS bf16x8*)(lds + PG8_SA(b, h) + aoff + m * 2048 + k * 1024); } while (0)
; #define PG8_LDB(dst, b, h) do { _Pragma("unroll") for (int n = 0; n < 2; ++n) _Pragma("unroll") for (int k = 0; k < 2; ++k) dst[n][k] = *(const PG8_LAS bf16x8*)(lds + PG8_SB(b, h) + boff + n * 2048 + k * 1024); } while (0)
; #define PG8_MMA(ai, bj, At, Bt) do { __builtin_amdgcn_s_setprio(1); _Pragma("unroll") for (int m = 0; m < 4; ++m) _Pragma("unroll") for (int n = 0; n < 2; ++n) _Pragma("unroll") for (int k = 0; k < 2; ++k) \
;         acc[ai][bj][m][n] = __builtin_amdgcn_mfma_f32_16x16x32_bf16(Bt[n][k], At[m][k], acc[ai][bj][m][n], 0, 0, 0); __builtin_amdgcn_s_setprio(0); } while (0)
; #define PG8_WAIT_V(n) asm volatile("s_waitcnt vmcnt(" #n ")" ::: "memory")
; #define PG8_WAIT_L(n) asm volatile("s_waitcnt lgkmcnt(" #n ")" ::: "memory")
; #define PG8_BAR __builtin_amdgcn_s_barrier()
; #define PG8_SCHED __builtin_amdgcn_sched_barrier(0)
; template <class Epi, class Sched, bool ALIGN_EPI = false, bool SP2 = true>
; __device__ __forceinline__ void gemm_phase(PG8_LAS unsigned char* lds, const Gemm g, const Sched& S, const Epi& E) {
;     ...
;             PG8_WAIT_V(8); PG8_WAIT_L(0); PG8_BAR; PG8_MMA(1, 0, At, B0); PG8_MMA(1, 1, At, B1); PG8_BAR; PG8_SCHED;
;             PG8_LDB(B0, 1, 0); PG8_LDB(B1, 1, 1); PG8_SCHED; PG8_LDA(At, 1, 0); PG8_STAGE(PG8_SA(0, 1), a2 + hstepA, voffA);
;             PG8_WAIT_V(8); PG8_WAIT_L(0); PG8_BAR; PG8_MMA(0, 0, At, B0); PG8_MMA(0, 1, At, B1); PG8_BAR; PG8_SCHED;
;             PG8_LDA(At, 1, 1); PG8_STAGE(PG8_SB(1, 0), b3, voffB); PG8_STAGE(PG8_SB(1, 1), b3 + hstep, voffB); PG8_STAGE(PG8_SA(1, 0), a3, voffA);
	v_mfma_f32_16x16x32_bf16 v[60:63], v[134:137], v[166:169], v[60:63]
	v_mfma_f32_16x16x32_bf16 v[56:59], v[142:145], v[166:169], v[56:59]
	v_mfma_f32_16x16x32_bf16 v[44:47], v[134:137], v[180:183], v[44:47]
	v_mfma_f32_16x16x32_bf16 v[40:43], v[142:145], v[180:183], v[40:43]
	v_mfma_f32_16x16x32_bf16 v[28:31], v[134:137], v[188:191], v[28:31]
	v_mfma_f32_16x16x32_bf16 v[24:27], v[142:145], v[188:191], v[24:27]
	v_mfma_f32_16x16x32_bf16 v[12:15], v[134:137], v[204:207], v[12:15]
	v_mfma_f32_16x16x32_bf16 v[8:11], v[142:145], v[204:207], v[8:11]
	v_mfma_f32_16x16x32_bf16 v[60:63], v[138:141], v[176:179], v[60:63]
	v_mfma_f32_16x16x32_bf16 v[56:59], v[146:149], v[176:179], v[56:59]
	v_mfma_f32_16x16x32_bf16 v[44:47], v[138:141], v[184:187], v[44:47]
	v_mfma_f32_16x16x32_bf16 v[40:43], v[146:149], v[184:187], v[40:43]
	v_mfma_f32_16x16x32_bf16 v[28:31], v[138:141], v[200:203], v[28:31]
	v_mfma_f32_16x16x32_bf16 v[24:27], v[146:149], v[200:203], v[24:27]
	v_mfma_f32_16x16x32_bf16 v[12:15], v[138:141], v[208:211], v[12:15]
	v_mfma_f32_16x16x32_bf16 v[8:11], v[146:149], v[208:211], v[8:11]
	s_setprio 0
	s_setprio 1
	v_mfma_f32_16x16x32_bf16 v[52:55], v[150:153], v[166:169], v[52:55]
	v_mfma_f32_16x16x32_bf16 v[48:51], v[158:161], v[166:169], v[48:51]
	v_mfma_f32_16x16x32_bf16 v[36:39], v[150:153], v[180:183], v[36:39]
	v_mfma_f32_16x16x32_bf16 v[32:35], v[158:161], v[180:183], v[32:35]
	v_mfma_f32_16x16x32_bf16 v[20:23], v[150:153], v[188:191], v[20:23]
	v_mfma_f32_16x16x32_bf16 v[16:19], v[158:161], v[188:191], v[16:19]
	v_mfma_f32_16x16x32_bf16 v[4:7], v[150:153], v[204:207], v[4:7]
	v_mfma_f32_16x16x32_bf16 v[0:3], v[158:161], v[204:207], v[0:3]
	v_mfma_f32_16x16x32_bf16 v[52:55], v[154:157], v[176:179], v[52:55]
	v_mfma_f32_16x16x32_bf16 v[48:51], v[162:165], v[176:179], v[48:51]
	v_mfma_f32_16x16x32_bf16 v[36:39], v[154:157], v[184:187], v[36:39]
	v_mfma_f32_16x16x32_bf16 v[32:35], v[162:165], v[184:187], v[32:35]
	v_mfma_f32_16x16x32_bf16 v[20:23], v[154:157], v[200:203], v[20:23]
	v_mfma_f32_16x16x32_bf16 v[16:19], v[162:165], v[200:203], v[16:19]
	v_mfma_f32_16x16x32_bf16 v[4:7], v[154:157], v[208:211], v[4:7]
	v_mfma_f32_16x16x32_bf16 v[0:3], v[162:165], v[208:211], v[0:3]
	s_setprio 0
	s_barrier
	s_add_i32 s4, 0, 0x18000
	s_add_i32 s5, 0, 0x1c000
	v_add_u32_e32 v146, s4, v173
	v_add_u32_e32 v162, s5, v173
	ds_read_b128 v[134:137], v146
	ds_read_b128 v[138:141], v146 offset:1024
	ds_read_b128 v[142:145], v146 offset:2048
	ds_read_b128 v[146:149], v146 offset:3072
	ds_read_b128 v[150:153], v162
	ds_read_b128 v[154:157], v162 offset:1024
	ds_read_b128 v[158:161], v162 offset:2048
	ds_read_b128 v[162:165], v162 offset:3072
	s_add_u32 s14, s84, 0x40000
	s_addc_u32 s15, s85, 0
	s_mov_b32 m0, s35
	v_lshl_add_u64 v[216:217], s[14:15], 0, v[194:195]
	ds_read_b128 v[166:169], v175 offset:32768
	ds_read_b128 v[176:179], v175 offset:33792
	ds_read_b128 v[180:183], v175 offset:34816
	ds_read_b128 v[184:187], v175 offset:35840
	ds_read_b128 v[188:191], v175 offset:36864
	ds_read_b128 v[200:203], v175 offset:37888
	ds_read_b128 v[204:207], v175 offset:38912
	ds_read_b128 v[208:211], v175 offset:39936
	global_load_lds_dwordx4 v[216:217], off
	v_lshl_add_u64 v[216:217], s[14:15], 0, v[128:129]
	s_mov_b32 m0, s49
	s_nop 0
	global_load_lds_dwordx4 v[216:217], off
	s_waitcnt vmcnt(8)
	s_waitcnt lgkmcnt(0)
	s_setprio 1
	s_barrier
	v_mfma_f32_16x16x32_bf16 v[124:127], v[134:137], v[166:169], v[124:127]
	v_mfma_f32_16x16x32_bf16 v[120:123], v[142:145], v[166:169], v[120:123]
	v_mfma_f32_16x16x32_bf16 v[108:111], v[134:137], v[180:183], v[108:111]
	v_mfma_f32_16x16x32_bf16 v[104:107], v[142:145], v[180:183], v[104:107]
	v_mfma_f32_16x16x32_bf16 v[92:95], v[134:137], v[188:191], v[92:95]
	v_mfma_f32_16x16x32_bf16 v[88:91], v[142:145], v[188:191], v[88:91]
	v_mfma_f32_16x16x32_bf16 v[76:79], v[134:137], v[204:207], v[76:79]
	v_mfma_f32_16x16x32_bf16 v[72:75], v[142:145], v[204:207], v[72:75]
	v_mfma_f32_16x16x32_bf16 v[124:127], v[138:141], v[176:179], v[124:127]
	v_mfma_f32_16x16x32_bf16 v[120:123], v[146:149], v[176:179], v[120:123]
	v_mfma_f32_16x16x32_bf16 v[108:111], v[138:141], v[184:187], v[108:111]
	v_mfma_f32_16x16x32_bf16 v[104:107], v[146:149], v[184:187], v[104:107]
	v_mfma_f32_16x16x32_bf16 v[92:95], v[138:141], v[200:203], v[92:95]
	v_mfma_f32_16x16x32_bf16 v[88:91], v[146:149], v[200:203], v[88:91]
	v_mfma_f32_16x16x32_bf16 v[76:79], v[138:141], v[208:211], v[76:79]
	v_mfma_f32_16x16x32_bf16 v[72:75], v[146:149], v[208:211], v[72:75]
	s_setprio 0
	s_setprio 1
	v_mfma_f32_16x16x32_bf16 v[116:119], v[150:153], v[166:169], v[116:119]
	v_mfma_f32_16x16x32_bf16 v[112:115], v[158:161], v[166:169], v[112:115]
	v_mfma_f32_16x16x32_bf16 v[100:103], v[150:153], v[180:183], v[100:103]
	v_mfma_f32_16x16x32_bf16 v[96:99], v[158:161], v[180:183], v[96:99]
	v_mfma_f32_16x16x32_bf16 v[84:87], v[150:153], v[188:191], v[84:87]
	v_mfma_f32_16x16x32_bf16 v[80:83], v[158:161], v[188:191], v[80:83]
	v_mfma_f32_16x16x32_bf16 v[68:71], v[150:153], v[204:207], v[68:71]
	v_mfma_f32_16x16x32_bf16 v[64:67], v[158:161], v[204:207], v[64:67]
	v_mfma_f32_16x16x32_bf16 v[116:119], v[154:157], v[176:179], v[116:119]
	v_mfma_f32_16x16x32_bf16 v[112:115], v[162:165], v[176:179], v[112:115]
	v_mfma_f32_16x16x32_bf16 v[100:103], v[154:157], v[184:187], v[100:103]
	v_mfma_f32_16x16x32_bf16 v[96:99], v[162:165], v[184:187], v[96:99]
	v_mfma_f32_16x16x32_bf16 v[84:87], v[154:157], v[200:203], v[84:87]
	v_mfma_f32_16x16x32_bf16 v[80:83], v[162:165], v[200:203], v[80:83]
	v_mfma_f32_16x16x32_bf16 v[68:71], v[154:157], v[208:211], v[68:71]
	v_mfma_f32_16x16x32_bf16 v[64:67], v[162:165], v[208:211], v[64:67]
	s_setprio 0
	s_barrier
; #define PG8_STAGE(bufoff, gbase, voff) do { _Pragma("unroll") for (int _i = 0; _i < 2; ++_i) \
;         __builtin_amdgcn_global_load_lds((const unsigned*)((const char*)(gbase) + (voff)[_i]), (PG8_LAS unsigned*)(lds + (bufoff) + ldsw + _i * 8192), 16, 0, 0); } while (0)
; #define PG8_LDA(dst, b, h) do { _Pragma("unroll") for (int m = 0; m < 4; ++m) _Pragma("unroll") for (int k = 0; k < 2; ++k) dst[m][k] = *(const PG8_LAS bf16x8*)(lds + PG8_SA(b, h) + aoff + m * 2048 + k * 1024); } while (0)
; #define PG8_MMA(ai, bj, At, Bt) do { __builtin_amdgcn_s_setprio(1); _Pragma("unroll") for (int m = 0; m < 4; ++m) _Pragma("unroll") for (int n = 0; n < 2; ++n) _Pragma("unroll") for (int k = 0; k < 2; ++k) \
;         acc[ai][bj][m][n] = __builtin_amdgcn_mfma_f32_16x16x32_bf16(Bt[n][k], At[m][k], acc[ai][bj][m][n], 0, 0, 0); __builtin_amdgcn_s_setprio(0); } while (0)
; #define PG8_WAIT_V(n) asm volatile("s_waitcnt vmcnt(" #n ")" ::: "memory")
; #define PG8_WAIT_L(n) asm volatile("s_waitcnt lgkmcnt(" #n ")" ::: "memory")
; #define PG8_BAR __builtin_amdgcn_s_barrier()
; #define PG8_SCHED __builtin_amdgcn_sched_barrier(0)
; template <class Epi, class Sched, bool ALIGN_EPI = false, bool SP2 = true>
; __device__ __forceinline__ void gemm_phase(PG8_LAS unsigned char* lds, const Gemm g, const Sched& S, const Epi& E) {
;     ...
;         for (int t = 0; t < nt; t += 2) {
;     ...
;             PG8_LDA(At, 1, 1); PG8_STAGE(PG8_SB(1, 0), b3, voffB); PG8_STAGE(PG8_SB(1, 1), b3 + hstep, voffB); PG8_STAGE(PG8_SA(1, 0), a3, voffA);
;             PG8_WAIT_V(8); PG8_WAIT_L(0); PG8_BAR; PG8_MMA(1, 0, At, B0); PG8_MMA(1, 1, At, B1); PG8_BAR; PG8_SCHED;
	s_add_i32 s4, s4, s30
	v_lshl_add_u64 v[170:171], v[170:171], 0, s[18:19]
	s_mov_b32 m0, s4
	ds_read_b128 v[166:169], v175 offset:49152
	ds_read_b128 v[176:179], v175 offset:50176
	ds_read_b128 v[180:183], v175 offset:51200
	ds_read_b128 v[184:187], v175 offset:52224
	ds_read_b128 v[188:191], v175 offset:53248
	ds_read_b128 v[200:203], v175 offset:54272
	ds_read_b128 v[204:207], v175 offset:55296
	ds_read_b128 v[208:211], v175 offset:56320
	global_load_lds_dwordx4 v[170:171], off
	s_add_i32 m0, s4, 0x2000
	s_add_u32 s14, s52, 0x40080
	v_lshl_add_u64 v[170:171], v[198:199], 0, s[18:19]
	s_addc_u32 s15, s53, 0
	s_add_i32 s4, s5, s30
	global_load_lds_dwordx4 v[170:171], off
	v_lshl_add_u64 v[170:171], s[14:15], 0, v[194:195]
	s_mov_b32 m0, s4
	s_nop 0
	global_load_lds_dwordx4 v[170:171], off
	v_lshl_add_u64 v[170:171], s[14:15], 0, v[128:129]
	s_add_i32 m0, s4, 0x2000
	s_nop 0
	global_load_lds_dwordx4 v[170:171], off
	v_lshl_add_u64 v[170:171], v[212:213], 0, s[18:19]
	s_mov_b32 m0, s57
	s_nop 0
	global_load_lds_dwordx4 v[170:171], off
	v_lshl_add_u64 v[170:171], v[214:215], 0, s[18:19]
	s_mov_b32 m0, s59
	s_nop 0
	global_load_lds_dwordx4 v[170:171], off
	s_waitcnt vmcnt(8)
	s_waitcnt lgkmcnt(0)
	s_setprio 1
	s_barrier
	v_mfma_f32_16x16x32_bf16 v[60:63], v[134:137], v[166:169], v[60:63]
	v_mfma_f32_16x16x32_bf16 v[56:59], v[142:145], v[166:169], v[56:59]
	v_mfma_f32_16x16x32_bf16 v[44:47], v[134:137], v[180:183], v[44:47]
	v_mfma_f32_16x16x32_bf16 v[40:43], v[142:145], v[180:183], v[40:43]
	v_mfma_f32_16x16x32_bf16 v[28:31], v[134:137], v[188:191], v[28:31]
	v_mfma_f32_16x16x32_bf16 v[24:27], v[142:145], v[188:191], v[24:27]
	v_mfma_f32_16x16x32_bf16 v[12:15], v[134:137], v[204:207], v[12:15]
	v_mfma_f32_16x16x32_bf16 v[8:11], v[142:145], v[204:207], v[8:11]
	v_mfma_f32_16x16x32_bf16 v[60:63], v[138:141], v[176:179], v[60:63]
	v_mfma_f32_16x16x32_bf16 v[56:59], v[146:149], v[176:179], v[56:59]
	v_mfma_f32_16x16x32_bf16 v[44:47], v[138:141], v[184:187], v[44:47]
	v_mfma_f32_16x16x32_bf16 v[40:43], v[146:149], v[184:187], v[40:43]
	v_mfma_f32_16x16x32_bf16 v[28:31], v[138:141], v[200:203], v[28:31]
	v_mfma_f32_16x16x32_bf16 v[24:27], v[146:149], v[200:203], v[24:27]
	v_mfma_f32_16x16x32_bf16 v[12:15], v[138:141], v[208:211], v[12:15]
	v_mfma_f32_16x16x32_bf16 v[8:11], v[146:149], v[208:211], v[8:11]
	s_setprio 0
	s_setprio 1
	v_mfma_f32_16x16x32_bf16 v[52:55], v[150:153], v[166:169], v[52:55]
	v_mfma_f32_16x16x32_bf16 v[48:51], v[158:161], v[166:169], v[48:51]
	v_mfma_f32_16x16x32_bf16 v[36:39], v[150:153], v[180:183], v[36:39]
	v_mfma_f32_16x16x32_bf16 v[32:35], v[158:161], v[180:183], v[32:35]
	v_mfma_f32_16x16x32_bf16 v[20:23], v[150:153], v[188:191], v[20:23]
	v_mfma_f32_16x16x32_bf16 v[16:19], v[158:161], v[188:191], v[16:19]
	v_mfma_f32_16x16x32_bf16 v[4:7], v[150:153], v[204:207], v[4:7]
	v_mfma_f32_16x16x32_bf16 v[0:3], v[158:161], v[204:207], v[0:3]
	v_mfma_f32_16x16x32_bf16 v[52:55], v[154:157], v[176:179], v[52:55]
	v_mfma_f32_16x16x32_bf16 v[48:51], v[162:165], v[176:179], v[48:51]
	v_mfma_f32_16x16x32_bf16 v[36:39], v[154:157], v[184:187], v[36:39]
	v_mfma_f32_16x16x32_bf16 v[32:35], v[162:165], v[184:187], v[32:35]
	v_mfma_f32_16x16x32_bf16 v[20:23], v[154:157], v[200:203], v[20:23]
	v_mfma_f32_16x16x32_bf16 v[16:19], v[162:165], v[200:203], v[16:19]
	v_mfma_f32_16x16x32_bf16 v[4:7], v[154:157], v[208:211], v[4:7]
	v_mfma_f32_16x16x32_bf16 v[0:3], v[162:165], v[208:211], v[0:3]
	s_setprio 0
	s_barrier
	s_add_i32 s47, s47, 2
	s_add_u32 s50, s50, 0x100
	s_addc_u32 s51, s51, 0
	s_add_u32 s6, s6, 0x100
	s_addc_u32 s7, s7, 0
	s_cmp_gt_u32 s47, 13
	s_cbranch_scc0 .LBB0_745
	s_and_b64 vcc, exec, s[20:21]
	s_cbranch_vccz .LBB0_748
	s_barrier
;     __device__ __forceinline__ void operator()(const f32x4 (&acc)[2][2][4][2], const Unit& u, int wr, int wc, int fr, int fq) const {
;     ...
;             } else {
;                 u32x2 rw[4][2][2];
; #pragma unroll
;                 for (int m = 0; m < 4; ++m) {
;                     const bf16_t* bp = hb + (size_t)(row0 + ai * HALF + m * 16) * 1024 + col0;
; #pragma unroll
;                     for (int bj = 0; bj < 2; ++bj)
; #pragma unroll
;                         for (int n = 0; n < 2; ++n) rw[m][bj][n] = *(const u32x2*)(bp + bj * HALF + n * 16);
;                 }
; #pragma unroll
;                 for (int m = 0; m < 4; ++m)
; #pragma unroll
;                     for (int bj = 0; bj < 2; ++bj)
; #pragma unroll
;                         for (int n = 0; n < 2; ++n) { const u32x2 r = rw[m][bj][n];
;                             v[m][bj][n] = (f32x4){__builtin_bit_cast(float, r.x << 16), __builtin_bit_cast(float, r.x & 0xffff0000u), __builtin_bit_cast(float, r.y << 16), __builtin_bit_cast(float, r.y & 0xffff0000u)}; }
;             }
;             asm volatile("" ::: "memory");
; #pragma unroll
;             for (int m = 0; m < 4; ++m) {
;                 const int row = row0 + ai * HALF + m * 16;
;                 const size_t off = (size_t)row * 1024 + col0;
; #pragma unroll
;                 for (int bj = 0; bj < 2; ++bj)
; #pragma unroll
;                     for (int n = 0; n < 2; ++n) v[m][bj][n] = v[m][bj][n] + acc[ai][bj][m][n] * alpha;
;                 if (final_) {
;                     float* op = out + off;
; #pragma unroll
;                     for (int bj = 0; bj < 2; ++bj)
; #pragma unroll
;                         for (int n = 0; n < 2; ++n) *(f32x4*)(op + bj * HALF + n * 16) = v[m][bj][n];
;                 } else {
;                     float part = 0.f;
; #pragma unroll
;                     for (int bj = 0; bj < 2; ++bj)
; #pragma unroll
;                         for (int n = 0; n < 2; ++n) {
;                             const f32x4 x = v[m][bj][n];
;                             u32x2 w; w.x = cvt_pk_bf16(x[0], x[1]); w.y = cvt_pk_bf16(x[2], x[3]);
;                             *(u32x2*)(hb + off + bj * HALF + n * 16) = w;
;                             part += (x[0] * x[0] + x[1] * x[1]) + (x[2] * x[2] + x[3] * x[3]);
;                         }
;                     part += __shfl_xor(part, 16); part += __shfl_xor(part, 32);
.LBB0_748:
	v_lshl_or_b32 v134, s46, 8, v174
	v_lshl_add_u32 v170, s48, 8, v172
	v_ashrrev_i32_e32 v135, 31, v134
	v_lshlrev_b64 v[176:177], 1, v[134:135]
	v_ashrrev_i32_e32 v171, 31, v170
	v_lshl_add_u64 v[136:137], s[54:55], 0, v[176:177]
	v_lshlrev_b64 v[138:139], 11, v[170:171]
	v_lshl_add_u64 v[140:141], v[136:137], 0, v[138:139]
	global_load_dwordx2 v[178:179], v[140:141], off
	global_load_dwordx2 v[180:181], v[140:141], off offset:32
	global_load_dwordx2 v[182:183], v[140:141], off offset:256
	global_load_dwordx2 v[184:185], v[140:141], off offset:288
	v_or_b32_e32 v140, 16, v170
	v_ashrrev_i32_e32 v141, 31, v140
	v_lshlrev_b64 v[160:161], 11, v[140:141]
	v_lshl_add_u64 v[140:141], v[136:137], 0, v[160:161]
	global_load_dwordx2 v[168:169], v[140:141], off
	global_load_dwordx2 v[166:167], v[140:141], off offset:32
	global_load_dwordx2 v[164:165], v[140:141], off offset:256
	global_load_dwordx2 v[162:163], v[140:141], off offset:288
	v_or_b32_e32 v140, 32, v170
	v_ashrrev_i32_e32 v141, 31, v140
	v_lshlrev_b64 v[150:151], 11, v[140:141]
	v_lshl_add_u64 v[140:141], v[136:137], 0, v[150:151]
	global_load_dwordx2 v[158:159], v[140:141], off
	global_load_dwordx2 v[156:157], v[140:141], off offset:32
	global_load_dwordx2 v[154:155], v[140:141], off offset:256
	global_load_dwordx2 v[152:153], v[140:141], off offset:288
	v_or_b32_e32 v140, 48, v170
	v_ashrrev_i32_e32 v141, 31, v140
	v_lshlrev_b64 v[140:141], 11, v[140:141]
	v_lshl_add_u64 v[142:143], v[136:137], 0, v[140:141]
	global_load_dwordx2 v[148:149], v[142:143], off
	global_load_dwordx2 v[146:147], v[142:143], off offset:32
	global_load_dwordx2 v[144:145], v[142:143], off offset:256
	s_nop 0
	global_load_dwordx2 v[142:143], v[142:143], off offset:288
	v_lshl_add_u64 v[214:215], v[136:137], 0, v[138:139]
	s_mov_b64 s[4:5], 0x40000
	v_lshl_add_u64 v[216:217], v[214:215], 0, s[4:5]
	global_load_dwordx2 v[218:219], v[216:217], off
	global_load_dwordx2 v[220:221], v[216:217], off offset:32
	global_load_dwordx2 v[222:223], v[216:217], off offset:256
	global_load_dwordx2 v[224:225], v[216:217], off offset:288
	s_mov_b64 s[4:5], 0x48000
	v_lshl_add_u64 v[216:217], v[214:215], 0, s[4:5]
	global_load_dwordx2 v[226:227], v[216:217], off
	global_load_dwordx2 v[228:229], v[216:217], off offset:32
	global_load_dwordx2 v[234:235], v[216:217], off offset:256
	global_load_dwordx2 v[236:237], v[216:217], off offset:288
	s_mov_b64 s[4:5], 0x50000
	v_lshl_add_u64 v[216:217], v[214:215], 0, s[4:5]
	global_load_dwordx2 v[238:239], v[216:217], off
	global_load_dwordx2 v[240:241], v[216:217], off offset:32
	global_load_dwordx2 v[242:243], v[216:217], off offset:256
	global_load_dwordx2 v[244:245], v[216:217], off offset:288
	s_mov_b64 s[4:5], 0x58000
	v_lshl_add_u64 v[216:217], v[214:215], 0, s[4:5]
	global_load_dwordx2 v[246:247], v[216:217], off
	global_load_dwordx2 v[248:249], v[216:217], off offset:32
	global_load_dwordx2 v[250:251], v[216:217], off offset:256
	global_load_dwordx2 v[212:213], v[216:217], off offset:288
	s_waitcnt vmcnt(16)
	v_lshlrev_b32_e32 v186, 16, v178
	v_and_b32_e32 v187, 0xffff0000, v178
	v_lshlrev_b32_e32 v178, 16, v179
	v_and_b32_e32 v179, 0xffff0000, v179
	v_pk_add_f32 v[124:125], v[124:125], v[186:187]
	v_lshlrev_b32_e32 v188, 16, v180
	v_and_b32_e32 v189, 0xffff0000, v180
	v_lshlrev_b32_e32 v180, 16, v181
	v_and_b32_e32 v181, 0xffff0000, v181
	v_pk_add_f32 v[126:127], v[126:127], v[178:179]
	v_cvt_pk_bf16_f32 v178, v124, v125
	v_mul_f32_e32 v125, v125, v125
	v_pk_add_f32 v[122:123], v[122:123], v[180:181]
	v_lshl_add_u64 v[180:181], s[54:55], 0, v[138:139]
	v_fmac_f32_e32 v125, v124, v124
	v_mul_f32_e32 v124, v127, v127
	v_pk_add_f32 v[120:121], v[120:121], v[188:189]
	v_lshl_add_u64 v[176:177], v[180:181], 0, v[176:177]
	v_fmac_f32_e32 v124, v126, v126
	v_cvt_pk_bf16_f32 v179, v126, v127
	global_store_dwordx2 v[176:177], v[178:179], off
	v_add_f32_e32 v126, v125, v124
	v_cvt_pk_bf16_f32 v124, v120, v121
	v_mul_f32_e32 v121, v121, v121
	v_fmac_f32_e32 v121, v120, v120
	v_mul_f32_e32 v120, v123, v123
	v_lshlrev_b32_e32 v190, 16, v182
	v_and_b32_e32 v191, 0xffff0000, v182
	v_fmac_f32_e32 v120, v122, v122
	v_lshlrev_b32_e32 v182, 16, v183
	v_and_b32_e32 v183, 0xffff0000, v183
	v_pk_add_f32 v[116:117], v[116:117], v[190:191]
	v_add_f32_e32 v120, v121, v120
	v_pk_add_f32 v[118:119], v[118:119], v[182:183]
	v_cvt_pk_bf16_f32 v125, v122, v123
	global_store_dwordx2 v[176:177], v[124:125], off offset:32
	v_add_f32_e32 v122, v126, v120
	v_cvt_pk_bf16_f32 v120, v116, v117
	v_mul_f32_e32 v117, v117, v117
	v_fmac_f32_e32 v117, v116, v116
	v_mul_f32_e32 v116, v119, v119
	v_lshlrev_b32_e32 v198, 16, v184
	v_and_b32_e32 v199, 0xffff0000, v184
	v_fmac_f32_e32 v116, v118, v118
	v_lshlrev_b32_e32 v184, 16, v185
	v_and_b32_e32 v185, 0xffff0000, v185
	v_pk_add_f32 v[112:113], v[112:113], v[198:199]
	v_add_f32_e32 v116, v117, v116
	v_pk_add_f32 v[114:115], v[114:115], v[184:185]
	v_cvt_pk_bf16_f32 v121, v118, v119
	global_store_dwordx2 v[176:177], v[120:121], off offset:256
	v_add_f32_e32 v118, v122, v116
	v_cvt_pk_bf16_f32 v116, v112, v113
	v_mul_f32_e32 v113, v113, v113
	v_fmac_f32_e32 v113, v112, v112
	v_mul_f32_e32 v112, v115, v115
	v_cvt_pk_bf16_f32 v117, v114, v115
	v_fmac_f32_e32 v112, v114, v114
	v_and_b32_e32 v114, 64, v230
	v_add_f32_e32 v112, v113, v112
	v_xor_b32_e32 v113, 16, v230
	v_add_u32_e32 v115, 64, v114
	v_cmp_lt_i32_e32 vcc, v113, v115
	v_add_f32_e32 v112, v118, v112
	global_store_dwordx2 v[176:177], v[116:117], off offset:288
	v_cndmask_b32_e32 v113, v230, v113, vcc
	v_lshlrev_b32_e32 v114, 2, v113
	ds_bpermute_b32 v113, v114, v112
	s_waitcnt lgkmcnt(0)
	v_add_f32_e32 v116, v112, v113
	v_xor_b32_e32 v112, 32, v230
	v_cmp_lt_i32_e32 vcc, v112, v115
	s_nop 1
	v_cndmask_b32_e32 v112, v230, v112, vcc
	v_lshlrev_b32_e32 v115, 2, v112
	ds_bpermute_b32 v117, v115, v116
	v_lshl_add_u64 v[112:113], v[170:171], 3, s[10:11]
	s_and_saveexec_b64 s[46:47], s[36:37]
	s_cbranch_execz .LBB0_750
	s_waitcnt lgkmcnt(0)
	v_add_f32_e32 v116, v116, v117
	v_mul_f32_e32 v116, 0x4b800000, v116
	v_trunc_f32_e32 v116, v116
	v_mul_f32_e32 v117, 0x2f800000, v116
	v_floor_f32_e32 v117, v117
	v_fmac_f32_e32 v116, 0xcf800000, v117
	v_cvt_u32_f32_e32 v116, v116
	v_cvt_u32_f32_e32 v117, v117
	global_atomic_add_x2 v[112:113], v[116:117], off

; __device__ __forceinline__ unsigned cvt_pk_bf16(float lo, float hi) { unsigned r; asm volatile("v_cvt_pk_bf16_f32 %0, %1, %2" : "=v"(r) : "v"(lo), "v"(hi)); return r; }
; __device__ __forceinline__ void ssq_add(ssq_t* p, float part) { atomicAdd(p, (ssq_t)(part * 16777216.0f)); }
;     __device__ __forceinline__ void operator()(const f32x4 (&acc)[2][2][4][2], const Unit& u, int wr, int wc, int fr, int fq) const {
;     ...
;             for (int m = 0; m < 4; ++m) {
;                 const int row = row0 + ai * HALF + m * 16;
;                 const size_t off = (size_t)row * 1024 + col0;
; #pragma unroll
;                 for (int bj = 0; bj < 2; ++bj)
; #pragma unroll
;                     for (int n = 0; n < 2; ++n) v[m][bj][n] = v[m][bj][n] + acc[ai][bj][m][n] * alpha;
;                 if (final_) {
;                     float* op = out + off;
; #pragma unroll
;                     for (int bj = 0; bj < 2; ++bj)
; #pragma unroll
;                         for (int n = 0; n < 2; ++n) *(f32x4*)(op + bj * HALF + n * 16) = v[m][bj][n];
;                 } else {
;                     float part = 0.f;
; #pragma unroll
;                     for (int bj = 0; bj < 2; ++bj)
; #pragma unroll
;                         for (int n = 0; n < 2; ++n) {
;                             const f32x4 x = v[m][bj][n];
;                             u32x2 w; w.x = cvt_pk_bf16(x[0], x[1]); w.y = cvt_pk_bf16(x[2], x[3]);
;                             *(u32x2*)(hb + off + bj * HALF + n * 16) = w;
;                             part += (x[0] * x[0] + x[1] * x[1]) + (x[2] * x[2] + x[3] * x[3]);
;                         }
;                     part += __shfl_xor(part, 16); part += __shfl_xor(part, 32);
;                     if (fq == 0) ssq_add(ssq_out + row, part);
.LBB0_756:
	s_or_b64 exec, exec, s[46:47]
	s_mov_b64 s[4:5], 0x40000
	v_lshl_add_u64 v[94:95], v[138:139], 0, s[4:5]
	s_waitcnt lgkmcnt(0)
	v_lshl_add_u64 v[64:65], v[136:137], 0, v[94:95]
	s_mov_b64 s[4:5], 0x48000
	v_lshl_add_u64 v[84:85], v[138:139], 0, s[4:5]
	s_mov_b64 s[4:5], 0x50000
	v_lshl_add_u64 v[74:75], v[138:139], 0, s[4:5]
	s_mov_b64 s[4:5], 0x58000
	v_lshl_add_u64 v[64:65], v[138:139], 0, s[4:5]
	v_lshl_add_u64 v[66:67], v[136:137], 0, v[84:85]
	v_lshl_add_u64 v[68:69], v[136:137], 0, v[74:75]
	v_lshl_add_u64 v[104:105], v[136:137], 0, v[64:65]
	v_lshl_add_u64 v[94:95], s[54:55], 0, v[94:95]
	v_lshl_add_u64 v[94:95], v[134:135], 1, v[94:95]
	s_waitcnt vmcnt(20)
	v_lshlrev_b32_e32 v104, 16, v218
	v_and_b32_e32 v105, 0xffff0000, v218
	v_lshlrev_b32_e32 v96, 16, v219
	v_and_b32_e32 v97, 0xffff0000, v219
	v_lshlrev_b32_e32 v106, 16, v220
	v_and_b32_e32 v107, 0xffff0000, v220
	v_lshlrev_b32_e32 v98, 16, v221
	v_and_b32_e32 v99, 0xffff0000, v221
	v_lshlrev_b32_e32 v108, 16, v222
	v_and_b32_e32 v109, 0xffff0000, v222
	v_lshlrev_b32_e32 v100, 16, v223
	v_and_b32_e32 v101, 0xffff0000, v223
	v_lshlrev_b32_e32 v110, 16, v224
	v_and_b32_e32 v111, 0xffff0000, v224
	v_pk_add_f32 v[62:63], v[62:63], v[96:97]
	v_pk_add_f32 v[60:61], v[60:61], v[104:105]
	v_pk_add_f32 v[58:59], v[58:59], v[98:99]
	v_pk_add_f32 v[56:57], v[56:57], v[106:107]
	v_lshlrev_b32_e32 v102, 16, v225
	v_and_b32_e32 v103, 0xffff0000, v225
	v_pk_add_f32 v[54:55], v[54:55], v[100:101]
	v_pk_add_f32 v[52:53], v[52:53], v[108:109]
	v_pk_add_f32 v[96:97], v[48:49], v[110:111]
	v_cvt_pk_bf16_f32 v48, v60, v61
	v_cvt_pk_bf16_f32 v49, v62, v63
	v_mul_f32_e32 v61, v61, v61
	v_mul_f32_e32 v63, v63, v63
	v_mul_f32_e32 v98, v57, v57
	v_mul_f32_e32 v99, v59, v59
	v_pk_add_f32 v[50:51], v[50:51], v[102:103]
	v_mul_f32_e32 v100, v53, v53
	v_mul_f32_e32 v101, v55, v55
	v_fmac_f32_e32 v61, v60, v60
	v_fmac_f32_e32 v63, v62, v62
	v_fmac_f32_e32 v98, v56, v56
	v_fmac_f32_e32 v99, v58, v58
	v_mul_f32_e32 v102, v97, v97
	v_mul_f32_e32 v103, v51, v51
	global_store_dwordx2 v[94:95], v[48:49], off
	v_cvt_pk_bf16_f32 v48, v56, v57
	v_fmac_f32_e32 v100, v52, v52
	v_fmac_f32_e32 v101, v54, v54
	v_add_f32_e32 v49, v61, v63
	v_add_f32_e32 v56, v98, v99
	v_fmac_f32_e32 v102, v96, v96
	v_fmac_f32_e32 v103, v50, v50
	v_add_f32_e32 v57, v100, v101
	v_add_f32_e32 v49, v49, v56
	v_add_f32_e32 v49, v49, v57
	v_add_f32_e32 v56, v102, v103
	v_add_f32_e32 v56, v49, v56
	ds_bpermute_b32 v57, v114, v56
	v_cvt_pk_bf16_f32 v49, v58, v59
	global_store_dwordx2 v[94:95], v[48:49], off offset:32
	v_cvt_pk_bf16_f32 v52, v52, v53
	v_cvt_pk_bf16_f32 v53, v54, v55
	s_waitcnt lgkmcnt(0)
	v_add_f32_e32 v48, v56, v57
	ds_bpermute_b32 v49, v115, v48
	global_store_dwordx2 v[94:95], v[52:53], off offset:256
	v_cvt_pk_bf16_f32 v52, v96, v97
	v_cvt_pk_bf16_f32 v53, v50, v51
	global_store_dwordx2 v[94:95], v[52:53], off offset:288
	s_and_saveexec_b64 s[46:47], s[36:37]
	s_cbranch_execz .LBB0_758
	s_waitcnt lgkmcnt(0)
	v_add_f32_e32 v48, v48, v49
	v_mul_f32_e32 v48, 0x4b800000, v48
	v_trunc_f32_e32 v48, v48
	v_mul_f32_e32 v49, 0x2f800000, v48
	v_floor_f32_e32 v49, v49
	v_fmac_f32_e32 v48, 0xcf800000, v49
	v_cvt_u32_f32_e32 v48, v48
	v_cvt_u32_f32_e32 v49, v49
	global_atomic_add_x2 v[112:113], v[48:49], off offset:1024
.LBB0_758:
	s_or_b64 exec, exec, s[46:47]
	v_lshlrev_b32_e32 v50, 16, v227
	v_and_b32_e32 v51, 0xffff0000, v227
	v_lshlrev_b32_e32 v48, 16, v226
	s_waitcnt lgkmcnt(0)
	v_and_b32_e32 v49, 0xffff0000, v226
	v_lshlrev_b32_e32 v60, 16, v236
	v_and_b32_e32 v61, 0xffff0000, v236
	v_pk_add_f32 v[46:47], v[46:47], v[50:51]
	v_lshl_add_u64 v[50:51], s[54:55], 0, v[84:85]
	v_pk_add_f32 v[44:45], v[44:45], v[48:49]
	v_pk_add_f32 v[48:49], v[32:33], v[60:61]
	v_cvt_pk_bf16_f32 v32, v44, v45
	v_cvt_pk_bf16_f32 v33, v46, v47
	v_lshl_add_u64 v[50:51], v[134:135], 1, v[50:51]
	v_lshlrev_b32_e32 v52, 16, v228
	v_and_b32_e32 v53, 0xffff0000, v228
	global_store_dwordx2 v[50:51], v[32:33], off
	v_mul_f32_e32 v32, v45, v45
	v_mul_f32_e32 v33, v47, v47
	v_lshlrev_b32_e32 v54, 16, v229
	v_and_b32_e32 v55, 0xffff0000, v229
	v_pk_add_f32 v[40:41], v[40:41], v[52:53]
	v_fmac_f32_e32 v32, v44, v44
	v_fmac_f32_e32 v33, v46, v46
	v_pk_add_f32 v[42:43], v[42:43], v[54:55]
	v_add_f32_e32 v33, v32, v33
	v_cvt_pk_bf16_f32 v32, v40, v41
	v_mul_f32_e32 v41, v41, v41
	v_fmac_f32_e32 v41, v40, v40
	v_mul_f32_e32 v40, v43, v43
	v_lshlrev_b32_e32 v56, 16, v234
	v_and_b32_e32 v57, 0xffff0000, v234
	v_lshlrev_b32_e32 v58, 16, v235
	v_and_b32_e32 v59, 0xffff0000, v235
	v_fmac_f32_e32 v40, v42, v42
	v_pk_add_f32 v[38:39], v[38:39], v[58:59]
	v_pk_add_f32 v[36:37], v[36:37], v[56:57]
	v_add_f32_e32 v40, v41, v40
	v_add_f32_e32 v33, v33, v40
	v_mul_f32_e32 v40, v37, v37
	v_mul_f32_e32 v41, v39, v39
	v_lshlrev_b32_e32 v62, 16, v237
	v_and_b32_e32 v63, 0xffff0000, v237
	v_fmac_f32_e32 v40, v36, v36
	v_fmac_f32_e32 v41, v38, v38
	v_pk_add_f32 v[34:35], v[34:35], v[62:63]
	v_add_f32_e32 v40, v40, v41
	v_add_f32_e32 v33, v33, v40
	v_mul_f32_e32 v40, v49, v49
	v_mul_f32_e32 v41, v35, v35
	v_fmac_f32_e32 v40, v48, v48
	v_fmac_f32_e32 v41, v34, v34
	v_add_f32_e32 v40, v40, v41
	v_add_f32_e32 v40, v33, v40
	ds_bpermute_b32 v41, v114, v40
	v_cvt_pk_bf16_f32 v33, v42, v43
	global_store_dwordx2 v[50:51], v[32:33], off offset:32
	v_cvt_pk_bf16_f32 v36, v36, v37
	v_cvt_pk_bf16_f32 v37, v38, v39
	s_waitcnt lgkmcnt(0)
	v_add_f32_e32 v32, v40, v41
	ds_bpermute_b32 v33, v115, v32
	global_store_dwordx2 v[50:51], v[36:37], off offset:256
	v_cvt_pk_bf16_f32 v36, v48, v49
	v_cvt_pk_bf16_f32 v37, v34, v35
	global_store_dwordx2 v[50:51], v[36:37], off offset:288
	s_and_saveexec_b64 s[46:47], s[36:37]
	s_cbranch_execz .LBB0_760
	s_waitcnt lgkmcnt(0)
	v_add_f32_e32 v32, v32, v33
	v_mul_f32_e32 v32, 0x4b800000, v32
	v_trunc_f32_e32 v32, v32
	v_mul_f32_e32 v33, 0x2f800000, v32
	v_floor_f32_e32 v33, v33
	v_fmac_f32_e32 v32, 0xcf800000, v33
	v_cvt_u32_f32_e32 v32, v32
	v_cvt_u32_f32_e32 v33, v33
	global_atomic_add_x2 v[112:113], v[32:33], off offset:1152
; __device__ __forceinline__ unsigned cvt_pk_bf16(float lo, float hi) { unsigned r; asm volatile("v_cvt_pk_bf16_f32 %0, %1, %2" : "=v"(r) : "v"(lo), "v"(hi)); return r; }
; __device__ __forceinline__ void ssq_add(ssq_t* p, float part) { atomicAdd(p, (ssq_t)(part * 16777216.0f)); }
;     __device__ __forceinline__ void operator()(const f32x4 (&acc)[2][2][4][2], const Unit& u, int wr, int wc, int fr, int fq) const {
;     ...
;             for (int m = 0; m < 4; ++m) {
;                 const int row = row0 + ai * HALF + m * 16;
;                 const size_t off = (size_t)row * 1024 + col0;
; #pragma unroll
;                 for (int bj = 0; bj < 2; ++bj)
; #pragma unroll
;                     for (int n = 0; n < 2; ++n) v[m][bj][n] = v[m][bj][n] + acc[ai][bj][m][n] * alpha;
;                 if (final_) {
;                     float* op = out + off;
; #pragma unroll
;                     for (int bj = 0; bj < 2; ++bj)
; #pragma unroll
;                         for (int n = 0; n < 2; ++n) *(f32x4*)(op + bj * HALF + n * 16) = v[m][bj][n];
;                 } else {
;                     float part = 0.f;
; #pragma unroll
;                     for (int bj = 0; bj < 2; ++bj)
; #pragma unroll
;                         for (int n = 0; n < 2; ++n) {
;                             const f32x4 x = v[m][bj][n];
;                             u32x2 w; w.x = cvt_pk_bf16(x[0], x[1]); w.y = cvt_pk_bf16(x[2], x[3]);
;                             *(u32x2*)(hb + off + bj * HALF + n * 16) = w;
;                             part += (x[0] * x[0] + x[1] * x[1]) + (x[2] * x[2] + x[3] * x[3]);
;                         }
;                     part += __shfl_xor(part, 16); part += __shfl_xor(part, 32);
;                     if (fq == 0) ssq_add(ssq_out + row, part);
.LBB0_760:
	s_or_b64 exec, exec, s[46:47]
	v_lshlrev_b32_e32 v34, 16, v239
	v_and_b32_e32 v35, 0xffff0000, v239
	v_lshlrev_b32_e32 v32, 16, v238
	s_waitcnt lgkmcnt(0)
	v_and_b32_e32 v33, 0xffff0000, v238
	v_lshlrev_b32_e32 v44, 16, v244
	v_and_b32_e32 v45, 0xffff0000, v244
	v_pk_add_f32 v[30:31], v[30:31], v[34:35]
	v_lshl_add_u64 v[34:35], s[54:55], 0, v[74:75]
	v_pk_add_f32 v[28:29], v[28:29], v[32:33]
	v_pk_add_f32 v[32:33], v[16:17], v[44:45]
	v_cvt_pk_bf16_f32 v16, v28, v29
	v_cvt_pk_bf16_f32 v17, v30, v31
	v_lshl_add_u64 v[34:35], v[134:135], 1, v[34:35]
	v_lshlrev_b32_e32 v36, 16, v240
	v_and_b32_e32 v37, 0xffff0000, v240
	global_store_dwordx2 v[34:35], v[16:17], off
	v_mul_f32_e32 v16, v29, v29
	v_mul_f32_e32 v17, v31, v31
	v_lshlrev_b32_e32 v38, 16, v241
	v_and_b32_e32 v39, 0xffff0000, v241
	v_pk_add_f32 v[24:25], v[24:25], v[36:37]
	v_fmac_f32_e32 v16, v28, v28
	v_fmac_f32_e32 v17, v30, v30
	v_pk_add_f32 v[26:27], v[26:27], v[38:39]
	v_add_f32_e32 v17, v16, v17
	v_cvt_pk_bf16_f32 v16, v24, v25
	v_mul_f32_e32 v25, v25, v25
	v_fmac_f32_e32 v25, v24, v24
	v_mul_f32_e32 v24, v27, v27
	v_lshlrev_b32_e32 v40, 16, v242
	v_and_b32_e32 v41, 0xffff0000, v242
	v_lshlrev_b32_e32 v42, 16, v243
	v_and_b32_e32 v43, 0xffff0000, v243
	v_fmac_f32_e32 v24, v26, v26
	v_pk_add_f32 v[22:23], v[22:23], v[42:43]
	v_pk_add_f32 v[20:21], v[20:21], v[40:41]
	v_add_f32_e32 v24, v25, v24
	v_add_f32_e32 v17, v17, v24
	v_mul_f32_e32 v24, v21, v21
	v_mul_f32_e32 v25, v23, v23
	v_lshlrev_b32_e32 v46, 16, v245
	v_and_b32_e32 v47, 0xffff0000, v245
	v_fmac_f32_e32 v24, v20, v20
	v_fmac_f32_e32 v25, v22, v22
	v_pk_add_f32 v[18:19], v[18:19], v[46:47]
	v_add_f32_e32 v24, v24, v25
	v_add_f32_e32 v17, v17, v24
	v_mul_f32_e32 v24, v33, v33
	v_mul_f32_e32 v25, v19, v19
	v_fmac_f32_e32 v24, v32, v32
	v_fmac_f32_e32 v25, v18, v18
	v_add_f32_e32 v24, v24, v25
	v_add_f32_e32 v24, v17, v24
	ds_bpermute_b32 v25, v114, v24
	v_cvt_pk_bf16_f32 v17, v26, v27
	global_store_dwordx2 v[34:35], v[16:17], off offset:32
	v_cvt_pk_bf16_f32 v20, v20, v21
	v_cvt_pk_bf16_f32 v21, v22, v23
	s_waitcnt lgkmcnt(0)
	v_add_f32_e32 v16, v24, v25
	ds_bpermute_b32 v17, v115, v16
	global_store_dwordx2 v[34:35], v[20:21], off offset:256
	v_cvt_pk_bf16_f32 v20, v32, v33
	v_cvt_pk_bf16_f32 v21, v18, v19
	global_store_dwordx2 v[34:35], v[20:21], off offset:288
	s_and_saveexec_b64 s[46:47], s[36:37]
	s_cbranch_execz .LBB0_762
	s_waitcnt lgkmcnt(0)
	v_add_f32_e32 v16, v16, v17
	v_mul_f32_e32 v16, 0x4b800000, v16
	v_trunc_f32_e32 v16, v16
	v_mul_f32_e32 v17, 0x2f800000, v16
	v_floor_f32_e32 v17, v17
	v_fmac_f32_e32 v16, 0xcf800000, v17
	v_cvt_u32_f32_e32 v16, v16
	v_cvt_u32_f32_e32 v17, v17
	global_atomic_add_x2 v[112:113], v[16:17], off offset:1280
.LBB0_762:
	s_or_b64 exec, exec, s[46:47]
	v_lshlrev_b32_e32 v18, 16, v247
	v_and_b32_e32 v19, 0xffff0000, v247
	v_lshlrev_b32_e32 v16, 16, v246
	s_waitcnt lgkmcnt(0)
	v_and_b32_e32 v17, 0xffff0000, v246
	v_lshlrev_b32_e32 v28, 16, v212
	v_and_b32_e32 v29, 0xffff0000, v212
	v_pk_add_f32 v[14:15], v[14:15], v[18:19]
	v_lshl_add_u64 v[18:19], s[54:55], 0, v[64:65]
	v_pk_add_f32 v[12:13], v[12:13], v[16:17]
	v_pk_add_f32 v[16:17], v[0:1], v[28:29]
	v_cvt_pk_bf16_f32 v0, v12, v13
	v_cvt_pk_bf16_f32 v1, v14, v15
	v_lshl_add_u64 v[18:19], v[134:135], 1, v[18:19]
	v_lshlrev_b32_e32 v20, 16, v248
	v_and_b32_e32 v21, 0xffff0000, v248
	global_store_dwordx2 v[18:19], v[0:1], off
	v_mul_f32_e32 v0, v13, v13
	v_mul_f32_e32 v1, v15, v15
	v_lshlrev_b32_e32 v22, 16, v249
	v_and_b32_e32 v23, 0xffff0000, v249
	v_pk_add_f32 v[8:9], v[8:9], v[20:21]
	v_fmac_f32_e32 v0, v12, v12
	v_fmac_f32_e32 v1, v14, v14
	v_pk_add_f32 v[10:11], v[10:11], v[22:23]
	v_add_f32_e32 v1, v0, v1
	v_cvt_pk_bf16_f32 v0, v8, v9
	v_mul_f32_e32 v9, v9, v9
	v_fmac_f32_e32 v9, v8, v8
	v_mul_f32_e32 v8, v11, v11
	v_lshlrev_b32_e32 v24, 16, v250
	v_and_b32_e32 v25, 0xffff0000, v250
	v_lshlrev_b32_e32 v26, 16, v251
	v_and_b32_e32 v27, 0xffff0000, v251
	v_fmac_f32_e32 v8, v10, v10
	v_pk_add_f32 v[6:7], v[6:7], v[26:27]
	v_pk_add_f32 v[4:5], v[4:5], v[24:25]
	v_add_f32_e32 v8, v9, v8
	v_add_f32_e32 v1, v1, v8
	v_mul_f32_e32 v8, v5, v5
	v_mul_f32_e32 v9, v7, v7
	v_lshlrev_b32_e32 v30, 16, v213
	v_and_b32_e32 v31, 0xffff0000, v213
	v_fmac_f32_e32 v8, v4, v4
	v_fmac_f32_e32 v9, v6, v6
	v_pk_add_f32 v[2:3], v[2:3], v[30:31]
	v_add_f32_e32 v8, v8, v9
	v_add_f32_e32 v1, v1, v8
	v_mul_f32_e32 v8, v17, v17
	v_mul_f32_e32 v9, v3, v3
	v_fmac_f32_e32 v8, v16, v16
	v_fmac_f32_e32 v9, v2, v2
	v_add_f32_e32 v8, v8, v9
	v_add_f32_e32 v8, v1, v8
	ds_bpermute_b32 v9, v114, v8
	v_cvt_pk_bf16_f32 v1, v10, v11
	global_store_dwordx2 v[18:19], v[0:1], off offset:32
	v_cvt_pk_bf16_f32 v4, v4, v5
	v_cvt_pk_bf16_f32 v5, v6, v7
	s_waitcnt lgkmcnt(0)
	v_add_f32_e32 v0, v8, v9
	ds_bpermute_b32 v1, v115, v0
	global_store_dwordx2 v[18:19], v[4:5], off offset:256
	v_cvt_pk_bf16_f32 v4, v16, v17
	v_cvt_pk_bf16_f32 v5, v2, v3
	global_store_dwordx2 v[18:19], v[4:5], off offset:288
	s_and_saveexec_b64 s[46:47], s[36:37]
	s_cbranch_execz .LBB0_764
	s_waitcnt lgkmcnt(0)
	v_add_f32_e32 v0, v0, v1
	v_mul_f32_e32 v0, 0x4b800000, v0
	v_trunc_f32_e32 v0, v0
	v_mul_f32_e32 v1, 0x2f800000, v0
	v_floor_f32_e32 v1, v1
	v_fmac_f32_e32 v0, 0xcf800000, v1
	v_cvt_u32_f32_e32 v0, v0
	v_cvt_u32_f32_e32 v1, v1
	global_atomic_add_x2 v[112:113], v[0:1], off offset:1408
